# branch-output epilogues K_Y1/K_Y2 hand-written per kind: all gate loads first, packed 1/255 scale, ubyte cvt + fma_mixlo/hi in place, second-half merged tiles requested as registers free
# baseline (speedup 1.0000x reference)
; template <unsigned D> __device__ __forceinline__ u32x4 rd8(u32x4 w) { w.x = rd<D>(w.x); w.y = rd<D>(w.y); w.z = rd<D>(w.z); w.w = rd<D>(w.w); return w; }
; __device__ __forceinline__ u32x4 pk8(const f32x4 v0, const f32x4 v1) { u32x4 w; w.x = pk_f16(v0[0], v0[1]); w.y = pk_f16(v0[2], v0[3]); w.z = pk_f16(v1[0], v1[1]); w.w = pk_f16(v1[2], v1[3]); return w; }
;     __device__ __forceinline__ void operator()(const f32x4 (&acc)[2][2][4][2], const GUnit& u, int wr, int wc, int fr, int fq, LAS unsigned char* lds) const {
;     ...
;         } else if (kind == K_Y1 || kind == K_Y2) {
;             f16* mrg = (f16*)(ws + B_MRG); const unsigned char* sg = (const unsigned char*)(ws + B_SG) + (kind == K_Y2 ? 1024 : 0);
; #pragma unroll
;             for (int ai = 0; ai < 2; ++ai) {
;                 u32x2 gwv[4][2]; u32x4 pv[4][2];
; #pragma unroll
;                 for (int m = 0; m < 4; ++m)
; #pragma unroll
;                     for (int bj = 0; bj < 2; ++bj) { const size_t row = (size_t)(grow0 + ai * 128 + m * 16); const int col = gcol0 + bj * 128;
;                         gwv[m][bj] = *(const u32x2*)(sg + row * 2048 + col);
;                         pv[m][bj] = kind == K_Y2 ? *(const u32x4*)(mrg + row * 1024 + col) : (u32x4){0u, 0u, 0u, 0u}; }
;                 asm volatile("" ::: "memory");
; #pragma unroll
;                 for (int m = 0; m < 4; ++m)
; #pragma unroll
;                     for (int bj = 0; bj < 2; ++bj) { const size_t row = (size_t)(grow0 + ai * 128 + m * 16); const int col = gcol0 + bj * 128;
;                         const u32x2 gw = gwv[m][bj]; constexpr float q8 = 1.0f / 255.0f;
;                         const f32x4 g0 = {(float)(gw.x & 255u) * q8, (float)((gw.x >> 8) & 255u) * q8, (float)((gw.x >> 16) & 255u) * q8, (float)(gw.x >> 24) * q8};
;                         const f32x4 g1 = {(float)(gw.y & 255u) * q8, (float)((gw.y >> 8) & 255u) * q8, (float)((gw.y >> 16) & 255u) * q8, (float)(gw.y >> 24) * q8};
;                         f32x4 p0, p1; unpk8(pv[m][bj], p0, p1);
;                         *(u32x4*)(mrg + row * 1024 + col) = rd8<D_AMIX>(pk8(acc[ai][bj][m][0] * g0 + p0, acc[ai][bj][m][1] * g1 + p1)); }
;                 asm volatile("" ::: "memory"); }
.LBB0_294:
	s_and_b64 vcc, exec, s[8:9]
	s_cbranch_vccz .LBB0_297
	s_cmp_eq_u32 s70, 6
	s_cselect_b32 s8, 0x400, 0
	v_readlane_b32 s10, v252, 5
	v_readlane_b32 s11, v252, 6
	s_add_u32 s10, s10, s8
	s_addc_u32 s11, s11, 0
	v_ashrrev_i32_e32 v181, 31, v180
	v_ashrrev_i32_e32 v183, 31, v182
	v_lshlrev_b64 v[134:135], 11, v[180:181]
	v_lshl_add_u64 v[132:133], s[10:11], 0, v[134:135]
	v_lshl_add_u64 v[132:133], v[132:133], 0, v[182:183]
	v_readlane_b32 s8, v252, 51
	v_readlane_b32 s9, v252, 52
	s_mov_b32 s98, 0x3b808081
	s_nop 1
	v_lshl_add_u64 v[134:135], s[8:9], 0, v[134:135]
	v_lshl_add_u64 v[134:135], v[182:183], 1, v[134:135]
	global_load_dwordx2 v[136:137], v[132:133], off
	global_load_dwordx2 v[138:139], v[132:133], off offset:128
	v_add_co_u32_e32 v194, vcc, 0x8000, v132
	v_addc_co_u32_e32 v195, vcc, 0, v133, vcc
	global_load_dwordx2 v[140:141], v[194:195], off
	global_load_dwordx2 v[142:143], v[194:195], off offset:128
	v_add_co_u32_e32 v194, vcc, 0x10000, v132
	v_addc_co_u32_e32 v195, vcc, 0, v133, vcc
	global_load_dwordx2 v[144:145], v[194:195], off
	global_load_dwordx2 v[146:147], v[194:195], off offset:128
	v_add_co_u32_e32 v194, vcc, 0x18000, v132
	v_addc_co_u32_e32 v195, vcc, 0, v133, vcc
	global_load_dwordx2 v[148:149], v[194:195], off
	global_load_dwordx2 v[150:151], v[194:195], off offset:128
	v_add_co_u32_e32 v194, vcc, 0x40000, v132
	v_addc_co_u32_e32 v195, vcc, 0, v133, vcc
	global_load_dwordx2 v[152:153], v[194:195], off
	global_load_dwordx2 v[154:155], v[194:195], off offset:128
	v_add_co_u32_e32 v194, vcc, 0x48000, v132
	v_addc_co_u32_e32 v195, vcc, 0, v133, vcc
	global_load_dwordx2 v[156:157], v[194:195], off
	global_load_dwordx2 v[158:159], v[194:195], off offset:128
	v_add_co_u32_e32 v194, vcc, 0x50000, v132
	v_addc_co_u32_e32 v195, vcc, 0, v133, vcc
	global_load_dwordx2 v[160:161], v[194:195], off
	global_load_dwordx2 v[162:163], v[194:195], off offset:128
	v_add_co_u32_e32 v194, vcc, 0x58000, v132
	v_addc_co_u32_e32 v195, vcc, 0, v133, vcc
	global_load_dwordx2 v[164:165], v[194:195], off
	global_load_dwordx2 v[166:167], v[194:195], off offset:128
	s_cmp_eq_u32 s70, 6
	s_cbranch_scc1 .Ly_two
	s_waitcnt vmcnt(15)
	v_pk_mul_f32 v[128:129], v[128:129], s[98:99] op_sel_hi:[1,0]
	v_pk_mul_f32 v[130:131], v[130:131], s[98:99] op_sel_hi:[1,0]
	v_pk_mul_f32 v[124:125], v[124:125], s[98:99] op_sel_hi:[1,0]
	v_pk_mul_f32 v[126:127], v[126:127], s[98:99] op_sel_hi:[1,0]
	v_cvt_f32_ubyte0_e32 v32, v136
	v_cvt_f32_ubyte1_e32 v181, v136
	v_fma_mixlo_f16 v168, v128, v32, 0
	v_fma_mixhi_f16 v168, v129, v181, 0
	v_cvt_f32_ubyte2_e32 v32, v136
	v_cvt_f32_ubyte3_e32 v181, v136
	v_fma_mixlo_f16 v169, v130, v32, 0
	v_fma_mixhi_f16 v169, v131, v181, 0
	v_cvt_f32_ubyte0_e32 v32, v137
	v_cvt_f32_ubyte1_e32 v181, v137
	v_fma_mixlo_f16 v170, v124, v32, 0
	v_fma_mixhi_f16 v170, v125, v181, 0
	v_cvt_f32_ubyte2_e32 v32, v137
	v_cvt_f32_ubyte3_e32 v181, v137
	v_fma_mixlo_f16 v171, v126, v32, 0
	v_fma_mixhi_f16 v171, v127, v181, 0
	v_add_u32_e32 v168, 0x100010, v168
	v_add_u32_e32 v169, 0x100010, v169
	v_add_u32_e32 v170, 0x100010, v170
	v_add_u32_e32 v171, 0x100010, v171
	v_and_b32_e32 v168, 0xffe0ffe0, v168
	v_and_b32_e32 v169, 0xffe0ffe0, v169
	v_and_b32_e32 v170, 0xffe0ffe0, v170
	v_and_b32_e32 v171, 0xffe0ffe0, v171
	global_store_dwordx4 v[134:135], v[168:171], off
	s_waitcnt vmcnt(15)
	v_pk_mul_f32 v[120:121], v[120:121], s[98:99] op_sel_hi:[1,0]
	v_pk_mul_f32 v[122:123], v[122:123], s[98:99] op_sel_hi:[1,0]
	v_pk_mul_f32 v[116:117], v[116:117], s[98:99] op_sel_hi:[1,0]
	v_pk_mul_f32 v[118:119], v[118:119], s[98:99] op_sel_hi:[1,0]
	v_cvt_f32_ubyte0_e32 v32, v138
	v_cvt_f32_ubyte1_e32 v181, v138
	v_fma_mixlo_f16 v172, v120, v32, 0
	v_fma_mixhi_f16 v172, v121, v181, 0
	v_cvt_f32_ubyte2_e32 v32, v138
	v_cvt_f32_ubyte3_e32 v181, v138
	v_fma_mixlo_f16 v173, v122, v32, 0
	v_fma_mixhi_f16 v173, v123, v181, 0
	v_cvt_f32_ubyte0_e32 v32, v139
	v_cvt_f32_ubyte1_e32 v181, v139
	v_fma_mixlo_f16 v174, v116, v32, 0
	v_fma_mixhi_f16 v174, v117, v181, 0
	v_cvt_f32_ubyte2_e32 v32, v139
	v_cvt_f32_ubyte3_e32 v181, v139
	v_fma_mixlo_f16 v175, v118, v32, 0
	v_fma_mixhi_f16 v175, v119, v181, 0
	v_add_u32_e32 v172, 0x100010, v172
	v_add_u32_e32 v173, 0x100010, v173
	v_add_u32_e32 v174, 0x100010, v174
	v_add_u32_e32 v175, 0x100010, v175
	v_and_b32_e32 v172, 0xffe0ffe0, v172
	v_and_b32_e32 v173, 0xffe0ffe0, v173
	v_and_b32_e32 v174, 0xffe0ffe0, v174
	v_and_b32_e32 v175, 0xffe0ffe0, v175
	global_store_dwordx4 v[134:135], v[172:175], off offset:256
	s_waitcnt vmcnt(15)
	v_pk_mul_f32 v[112:113], v[112:113], s[98:99] op_sel_hi:[1,0]
	v_pk_mul_f32 v[114:115], v[114:115], s[98:99] op_sel_hi:[1,0]
	v_pk_mul_f32 v[108:109], v[108:109], s[98:99] op_sel_hi:[1,0]
	v_pk_mul_f32 v[110:111], v[110:111], s[98:99] op_sel_hi:[1,0]
	v_cvt_f32_ubyte0_e32 v32, v140
	v_cvt_f32_ubyte1_e32 v181, v140
	v_fma_mixlo_f16 v176, v112, v32, 0
	v_fma_mixhi_f16 v176, v113, v181, 0
	v_cvt_f32_ubyte2_e32 v32, v140
	v_cvt_f32_ubyte3_e32 v181, v140
	v_fma_mixlo_f16 v177, v114, v32, 0
	v_fma_mixhi_f16 v177, v115, v181, 0
	v_cvt_f32_ubyte0_e32 v32, v141
	v_cvt_f32_ubyte1_e32 v181, v141
	v_fma_mixlo_f16 v178, v108, v32, 0
	v_fma_mixhi_f16 v178, v109, v181, 0
	v_cvt_f32_ubyte2_e32 v32, v141
	v_cvt_f32_ubyte3_e32 v181, v141
	v_fma_mixlo_f16 v179, v110, v32, 0
	v_fma_mixhi_f16 v179, v111, v181, 0
	v_add_u32_e32 v176, 0x100010, v176
	v_add_u32_e32 v177, 0x100010, v177
	v_add_u32_e32 v178, 0x100010, v178
	v_add_u32_e32 v179, 0x100010, v179
	v_and_b32_e32 v176, 0xffe0ffe0, v176
	v_and_b32_e32 v177, 0xffe0ffe0, v177
	v_and_b32_e32 v178, 0xffe0ffe0, v178
	v_and_b32_e32 v179, 0xffe0ffe0, v179
	v_add_co_u32_e32 v140, vcc, 0x8000, v134
	v_addc_co_u32_e32 v141, vcc, 0, v135, vcc
	global_store_dwordx4 v[140:141], v[176:179], off
	s_waitcnt vmcnt(15)
; template <unsigned D> __device__ __forceinline__ u32x4 rd8(u32x4 w) { w.x = rd<D>(w.x); w.y = rd<D>(w.y); w.z = rd<D>(w.z); w.w = rd<D>(w.w); return w; }
; __device__ __forceinline__ u32x4 pk8(const f32x4 v0, const f32x4 v1) { u32x4 w; w.x = pk_f16(v0[0], v0[1]); w.y = pk_f16(v0[2], v0[3]); w.z = pk_f16(v1[0], v1[1]); w.w = pk_f16(v1[2], v1[3]); return w; }
;     __device__ __forceinline__ void operator()(const f32x4 (&acc)[2][2][4][2], const GUnit& u, int wr, int wc, int fr, int fq, LAS unsigned char* lds) const {
;     ...
;                     for (int bj = 0; bj < 2; ++bj) { const size_t row = (size_t)(grow0 + ai * 128 + m * 16); const int col = gcol0 + bj * 128;
;                         gwv[m][bj] = *(const u32x2*)(sg + row * 2048 + col);
;                         pv[m][bj] = kind == K_Y2 ? *(const u32x4*)(mrg + row * 1024 + col) : (u32x4){0u, 0u, 0u, 0u}; }
;                 asm volatile("" ::: "memory");
; #pragma unroll
;                 for (int m = 0; m < 4; ++m)
; #pragma unroll
;                     for (int bj = 0; bj < 2; ++bj) { const size_t row = (size_t)(grow0 + ai * 128 + m * 16); const int col = gcol0 + bj * 128;
;                         const u32x2 gw = gwv[m][bj]; constexpr float q8 = 1.0f / 255.0f;
;                         const f32x4 g0 = {(float)(gw.x & 255u) * q8, (float)((gw.x >> 8) & 255u) * q8, (float)((gw.x >> 16) & 255u) * q8, (float)(gw.x >> 24) * q8};
;                         const f32x4 g1 = {(float)(gw.y & 255u) * q8, (float)((gw.y >> 8) & 255u) * q8, (float)((gw.y >> 16) & 255u) * q8, (float)(gw.y >> 24) * q8};
;                         f32x4 p0, p1; unpk8(pv[m][bj], p0, p1);
;                         *(u32x4*)(mrg + row * 1024 + col) = rd8<D_AMIX>(pk8(acc[ai][bj][m][0] * g0 + p0, acc[ai][bj][m][1] * g1 + p1)); }
;                 asm volatile("" ::: "memory"); }
	v_pk_mul_f32 v[104:105], v[104:105], s[98:99] op_sel_hi:[1,0]
	v_pk_mul_f32 v[106:107], v[106:107], s[98:99] op_sel_hi:[1,0]
	v_pk_mul_f32 v[100:101], v[100:101], s[98:99] op_sel_hi:[1,0]
	v_pk_mul_f32 v[102:103], v[102:103], s[98:99] op_sel_hi:[1,0]
	v_cvt_f32_ubyte0_e32 v32, v142
	v_cvt_f32_ubyte1_e32 v181, v142
	v_fma_mixlo_f16 v190, v104, v32, 0
	v_fma_mixhi_f16 v190, v105, v181, 0
	v_cvt_f32_ubyte2_e32 v32, v142
	v_cvt_f32_ubyte3_e32 v181, v142
	v_fma_mixlo_f16 v191, v106, v32, 0
	v_fma_mixhi_f16 v191, v107, v181, 0
	v_cvt_f32_ubyte0_e32 v32, v143
	v_cvt_f32_ubyte1_e32 v181, v143
	v_fma_mixlo_f16 v192, v100, v32, 0
	v_fma_mixhi_f16 v192, v101, v181, 0
	v_cvt_f32_ubyte2_e32 v32, v143
	v_cvt_f32_ubyte3_e32 v181, v143
	v_fma_mixlo_f16 v193, v102, v32, 0
	v_fma_mixhi_f16 v193, v103, v181, 0
	v_add_u32_e32 v190, 0x100010, v190
	v_add_u32_e32 v191, 0x100010, v191
	v_add_u32_e32 v192, 0x100010, v192
	v_add_u32_e32 v193, 0x100010, v193
	v_and_b32_e32 v190, 0xffe0ffe0, v190
	v_and_b32_e32 v191, 0xffe0ffe0, v191
	v_and_b32_e32 v192, 0xffe0ffe0, v192
	v_and_b32_e32 v193, 0xffe0ffe0, v193
	v_add_co_u32_e32 v142, vcc, 0x8000, v134
	v_addc_co_u32_e32 v143, vcc, 0, v135, vcc
	global_store_dwordx4 v[142:143], v[190:193], off offset:256
	s_waitcnt vmcnt(15)
	v_pk_mul_f32 v[96:97], v[96:97], s[98:99] op_sel_hi:[1,0]
	v_pk_mul_f32 v[98:99], v[98:99], s[98:99] op_sel_hi:[1,0]
	v_pk_mul_f32 v[92:93], v[92:93], s[98:99] op_sel_hi:[1,0]
	v_pk_mul_f32 v[94:95], v[94:95], s[98:99] op_sel_hi:[1,0]
	v_cvt_f32_ubyte0_e32 v32, v144
	v_cvt_f32_ubyte1_e32 v181, v144
	v_fma_mixlo_f16 v198, v96, v32, 0
	v_fma_mixhi_f16 v198, v97, v181, 0
	v_cvt_f32_ubyte2_e32 v32, v144
	v_cvt_f32_ubyte3_e32 v181, v144
	v_fma_mixlo_f16 v199, v98, v32, 0
	v_fma_mixhi_f16 v199, v99, v181, 0
	v_cvt_f32_ubyte0_e32 v32, v145
	v_cvt_f32_ubyte1_e32 v181, v145
	v_fma_mixlo_f16 v200, v92, v32, 0
	v_fma_mixhi_f16 v200, v93, v181, 0
	v_cvt_f32_ubyte2_e32 v32, v145
	v_cvt_f32_ubyte3_e32 v181, v145
	v_fma_mixlo_f16 v201, v94, v32, 0
	v_fma_mixhi_f16 v201, v95, v181, 0
	v_add_u32_e32 v198, 0x100010, v198
	v_add_u32_e32 v199, 0x100010, v199
	v_add_u32_e32 v200, 0x100010, v200
	v_add_u32_e32 v201, 0x100010, v201
	v_and_b32_e32 v198, 0xffe0ffe0, v198
	v_and_b32_e32 v199, 0xffe0ffe0, v199
	v_and_b32_e32 v200, 0xffe0ffe0, v200
	v_and_b32_e32 v201, 0xffe0ffe0, v201
	v_add_co_u32_e32 v144, vcc, 0x10000, v134
	v_addc_co_u32_e32 v145, vcc, 0, v135, vcc
	global_store_dwordx4 v[144:145], v[198:201], off
	s_waitcnt vmcnt(15)
	v_pk_mul_f32 v[88:89], v[88:89], s[98:99] op_sel_hi:[1,0]
	v_pk_mul_f32 v[90:91], v[90:91], s[98:99] op_sel_hi:[1,0]
	v_pk_mul_f32 v[84:85], v[84:85], s[98:99] op_sel_hi:[1,0]
	v_pk_mul_f32 v[86:87], v[86:87], s[98:99] op_sel_hi:[1,0]
	v_cvt_f32_ubyte0_e32 v32, v146
	v_cvt_f32_ubyte1_e32 v181, v146
	v_fma_mixlo_f16 v204, v88, v32, 0
	v_fma_mixhi_f16 v204, v89, v181, 0
	v_cvt_f32_ubyte2_e32 v32, v146
	v_cvt_f32_ubyte3_e32 v181, v146
	v_fma_mixlo_f16 v205, v90, v32, 0
	v_fma_mixhi_f16 v205, v91, v181, 0
	v_cvt_f32_ubyte0_e32 v32, v147
	v_cvt_f32_ubyte1_e32 v181, v147
	v_fma_mixlo_f16 v206, v84, v32, 0
	v_fma_mixhi_f16 v206, v85, v181, 0
	v_cvt_f32_ubyte2_e32 v32, v147
	v_cvt_f32_ubyte3_e32 v181, v147
	v_fma_mixlo_f16 v207, v86, v32, 0
	v_fma_mixhi_f16 v207, v87, v181, 0
	v_add_u32_e32 v204, 0x100010, v204
	v_add_u32_e32 v205, 0x100010, v205
	v_add_u32_e32 v206, 0x100010, v206
	v_add_u32_e32 v207, 0x100010, v207
	v_and_b32_e32 v204, 0xffe0ffe0, v204
	v_and_b32_e32 v205, 0xffe0ffe0, v205
	v_and_b32_e32 v206, 0xffe0ffe0, v206
	v_and_b32_e32 v207, 0xffe0ffe0, v207
	v_add_co_u32_e32 v146, vcc, 0x10000, v134
	v_addc_co_u32_e32 v147, vcc, 0, v135, vcc
	global_store_dwordx4 v[146:147], v[204:207], off offset:256
	s_waitcnt vmcnt(15)
	v_pk_mul_f32 v[80:81], v[80:81], s[98:99] op_sel_hi:[1,0]
	v_pk_mul_f32 v[82:83], v[82:83], s[98:99] op_sel_hi:[1,0]
	v_pk_mul_f32 v[76:77], v[76:77], s[98:99] op_sel_hi:[1,0]
	v_pk_mul_f32 v[78:79], v[78:79], s[98:99] op_sel_hi:[1,0]
	v_cvt_f32_ubyte0_e32 v32, v148
	v_cvt_f32_ubyte1_e32 v181, v148
	v_fma_mixlo_f16 v208, v80, v32, 0
	v_fma_mixhi_f16 v208, v81, v181, 0
	v_cvt_f32_ubyte2_e32 v32, v148
	v_cvt_f32_ubyte3_e32 v181, v148
	v_fma_mixlo_f16 v209, v82, v32, 0
	v_fma_mixhi_f16 v209, v83, v181, 0
	v_cvt_f32_ubyte0_e32 v32, v149
	v_cvt_f32_ubyte1_e32 v181, v149
	v_fma_mixlo_f16 v210, v76, v32, 0
	v_fma_mixhi_f16 v210, v77, v181, 0
	v_cvt_f32_ubyte2_e32 v32, v149
	v_cvt_f32_ubyte3_e32 v181, v149
	v_fma_mixlo_f16 v211, v78, v32, 0
	v_fma_mixhi_f16 v211, v79, v181, 0
	v_add_u32_e32 v208, 0x100010, v208
	v_add_u32_e32 v209, 0x100010, v209
	v_add_u32_e32 v210, 0x100010, v210
	v_add_u32_e32 v211, 0x100010, v211
	v_and_b32_e32 v208, 0xffe0ffe0, v208
	v_and_b32_e32 v209, 0xffe0ffe0, v209
	v_and_b32_e32 v210, 0xffe0ffe0, v210
	v_and_b32_e32 v211, 0xffe0ffe0, v211
	v_add_co_u32_e32 v148, vcc, 0x18000, v134
	v_addc_co_u32_e32 v149, vcc, 0, v135, vcc
	global_store_dwordx4 v[148:149], v[208:211], off
	s_waitcnt vmcnt(15)
	v_pk_mul_f32 v[72:73], v[72:73], s[98:99] op_sel_hi:[1,0]
	v_pk_mul_f32 v[74:75], v[74:75], s[98:99] op_sel_hi:[1,0]
	v_pk_mul_f32 v[68:69], v[68:69], s[98:99] op_sel_hi:[1,0]
	v_pk_mul_f32 v[70:71], v[70:71], s[98:99] op_sel_hi:[1,0]
	v_cvt_f32_ubyte0_e32 v32, v150
	v_cvt_f32_ubyte1_e32 v181, v150
	v_fma_mixlo_f16 v212, v72, v32, 0
	v_fma_mixhi_f16 v212, v73, v181, 0
	v_cvt_f32_ubyte2_e32 v32, v150
	v_cvt_f32_ubyte3_e32 v181, v150
	v_fma_mixlo_f16 v213, v74, v32, 0
	v_fma_mixhi_f16 v213, v75, v181, 0
	v_cvt_f32_ubyte0_e32 v32, v151
	v_cvt_f32_ubyte1_e32 v181, v151
	v_fma_mixlo_f16 v214, v68, v32, 0
	v_fma_mixhi_f16 v214, v69, v181, 0
	v_cvt_f32_ubyte2_e32 v32, v151
	v_cvt_f32_ubyte3_e32 v181, v151
	v_fma_mixlo_f16 v215, v70, v32, 0
	v_fma_mixhi_f16 v215, v71, v181, 0
	v_add_u32_e32 v212, 0x100010, v212
	v_add_u32_e32 v213, 0x100010, v213
	v_add_u32_e32 v214, 0x100010, v214
	v_add_u32_e32 v215, 0x100010, v215
	v_and_b32_e32 v212, 0xffe0ffe0, v212
	v_and_b32_e32 v213, 0xffe0ffe0, v213
	v_and_b32_e32 v214, 0xffe0ffe0, v214
	v_and_b32_e32 v215, 0xffe0ffe0, v215
	v_add_co_u32_e32 v150, vcc, 0x18000, v134
	v_addc_co_u32_e32 v151, vcc, 0, v135, vcc
	global_store_dwordx4 v[150:151], v[212:215], off offset:256
	s_waitcnt vmcnt(15)
; template <unsigned D> __device__ __forceinline__ u32x4 rd8(u32x4 w) { w.x = rd<D>(w.x); w.y = rd<D>(w.y); w.z = rd<D>(w.z); w.w = rd<D>(w.w); return w; }
; __device__ __forceinline__ u32x4 pk8(const f32x4 v0, const f32x4 v1) { u32x4 w; w.x = pk_f16(v0[0], v0[1]); w.y = pk_f16(v0[2], v0[3]); w.z = pk_f16(v1[0], v1[1]); w.w = pk_f16(v1[2], v1[3]); return w; }
;     __device__ __forceinline__ void operator()(const f32x4 (&acc)[2][2][4][2], const GUnit& u, int wr, int wc, int fr, int fq, LAS unsigned char* lds) const {
;     ...
;                     for (int bj = 0; bj < 2; ++bj) { const size_t row = (size_t)(grow0 + ai * 128 + m * 16); const int col = gcol0 + bj * 128;
;                         gwv[m][bj] = *(const u32x2*)(sg + row * 2048 + col);
;                         pv[m][bj] = kind == K_Y2 ? *(const u32x4*)(mrg + row * 1024 + col) : (u32x4){0u, 0u, 0u, 0u}; }
;                 asm volatile("" ::: "memory");
; #pragma unroll
;                 for (int m = 0; m < 4; ++m)
; #pragma unroll
;                     for (int bj = 0; bj < 2; ++bj) { const size_t row = (size_t)(grow0 + ai * 128 + m * 16); const int col = gcol0 + bj * 128;
;                         const u32x2 gw = gwv[m][bj]; constexpr float q8 = 1.0f / 255.0f;
;                         const f32x4 g0 = {(float)(gw.x & 255u) * q8, (float)((gw.x >> 8) & 255u) * q8, (float)((gw.x >> 16) & 255u) * q8, (float)(gw.x >> 24) * q8};
;                         const f32x4 g1 = {(float)(gw.y & 255u) * q8, (float)((gw.y >> 8) & 255u) * q8, (float)((gw.y >> 16) & 255u) * q8, (float)(gw.y >> 24) * q8};
;                         f32x4 p0, p1; unpk8(pv[m][bj], p0, p1);
;                         *(u32x4*)(mrg + row * 1024 + col) = rd8<D_AMIX>(pk8(acc[ai][bj][m][0] * g0 + p0, acc[ai][bj][m][1] * g1 + p1)); }
;                 asm volatile("" ::: "memory"); }
	v_pk_mul_f32 v[64:65], v[64:65], s[98:99] op_sel_hi:[1,0]
	v_pk_mul_f32 v[66:67], v[66:67], s[98:99] op_sel_hi:[1,0]
	v_pk_mul_f32 v[60:61], v[60:61], s[98:99] op_sel_hi:[1,0]
	v_pk_mul_f32 v[62:63], v[62:63], s[98:99] op_sel_hi:[1,0]
	v_cvt_f32_ubyte0_e32 v32, v152
	v_cvt_f32_ubyte1_e32 v181, v152
	v_fma_mixlo_f16 v168, v64, v32, 0
	v_fma_mixhi_f16 v168, v65, v181, 0
	v_cvt_f32_ubyte2_e32 v32, v152
	v_cvt_f32_ubyte3_e32 v181, v152
	v_fma_mixlo_f16 v169, v66, v32, 0
	v_fma_mixhi_f16 v169, v67, v181, 0
	v_cvt_f32_ubyte0_e32 v32, v153
	v_cvt_f32_ubyte1_e32 v181, v153
	v_fma_mixlo_f16 v170, v60, v32, 0
	v_fma_mixhi_f16 v170, v61, v181, 0
	v_cvt_f32_ubyte2_e32 v32, v153
	v_cvt_f32_ubyte3_e32 v181, v153
	v_fma_mixlo_f16 v171, v62, v32, 0
	v_fma_mixhi_f16 v171, v63, v181, 0
	v_add_u32_e32 v168, 0x100010, v168
	v_add_u32_e32 v169, 0x100010, v169
	v_add_u32_e32 v170, 0x100010, v170
	v_add_u32_e32 v171, 0x100010, v171
	v_and_b32_e32 v168, 0xffe0ffe0, v168
	v_and_b32_e32 v169, 0xffe0ffe0, v169
	v_and_b32_e32 v170, 0xffe0ffe0, v170
	v_and_b32_e32 v171, 0xffe0ffe0, v171
	v_add_co_u32_e32 v152, vcc, 0x40000, v134
	v_addc_co_u32_e32 v153, vcc, 0, v135, vcc
	global_store_dwordx4 v[152:153], v[168:171], off
	s_waitcnt vmcnt(15)
	v_pk_mul_f32 v[56:57], v[56:57], s[98:99] op_sel_hi:[1,0]
	v_pk_mul_f32 v[58:59], v[58:59], s[98:99] op_sel_hi:[1,0]
	v_pk_mul_f32 v[52:53], v[52:53], s[98:99] op_sel_hi:[1,0]
	v_pk_mul_f32 v[54:55], v[54:55], s[98:99] op_sel_hi:[1,0]
	v_cvt_f32_ubyte0_e32 v32, v154
	v_cvt_f32_ubyte1_e32 v181, v154
	v_fma_mixlo_f16 v172, v56, v32, 0
	v_fma_mixhi_f16 v172, v57, v181, 0
	v_cvt_f32_ubyte2_e32 v32, v154
	v_cvt_f32_ubyte3_e32 v181, v154
	v_fma_mixlo_f16 v173, v58, v32, 0
	v_fma_mixhi_f16 v173, v59, v181, 0
	v_cvt_f32_ubyte0_e32 v32, v155
	v_cvt_f32_ubyte1_e32 v181, v155
	v_fma_mixlo_f16 v174, v52, v32, 0
	v_fma_mixhi_f16 v174, v53, v181, 0
	v_cvt_f32_ubyte2_e32 v32, v155
	v_cvt_f32_ubyte3_e32 v181, v155
	v_fma_mixlo_f16 v175, v54, v32, 0
	v_fma_mixhi_f16 v175, v55, v181, 0
	v_add_u32_e32 v172, 0x100010, v172
	v_add_u32_e32 v173, 0x100010, v173
	v_add_u32_e32 v174, 0x100010, v174
	v_add_u32_e32 v175, 0x100010, v175
	v_and_b32_e32 v172, 0xffe0ffe0, v172
	v_and_b32_e32 v173, 0xffe0ffe0, v173
	v_and_b32_e32 v174, 0xffe0ffe0, v174
	v_and_b32_e32 v175, 0xffe0ffe0, v175
	v_add_co_u32_e32 v154, vcc, 0x40000, v134
	v_addc_co_u32_e32 v155, vcc, 0, v135, vcc
	global_store_dwordx4 v[154:155], v[172:175], off offset:256
	s_waitcnt vmcnt(15)
	v_pk_mul_f32 v[48:49], v[48:49], s[98:99] op_sel_hi:[1,0]
	v_pk_mul_f32 v[50:51], v[50:51], s[98:99] op_sel_hi:[1,0]
	v_pk_mul_f32 v[44:45], v[44:45], s[98:99] op_sel_hi:[1,0]
	v_pk_mul_f32 v[46:47], v[46:47], s[98:99] op_sel_hi:[1,0]
	v_cvt_f32_ubyte0_e32 v32, v156
	v_cvt_f32_ubyte1_e32 v181, v156
	v_fma_mixlo_f16 v176, v48, v32, 0
	v_fma_mixhi_f16 v176, v49, v181, 0
	v_cvt_f32_ubyte2_e32 v32, v156
	v_cvt_f32_ubyte3_e32 v181, v156
	v_fma_mixlo_f16 v177, v50, v32, 0
	v_fma_mixhi_f16 v177, v51, v181, 0
	v_cvt_f32_ubyte0_e32 v32, v157
	v_cvt_f32_ubyte1_e32 v181, v157
	v_fma_mixlo_f16 v178, v44, v32, 0
	v_fma_mixhi_f16 v178, v45, v181, 0
	v_cvt_f32_ubyte2_e32 v32, v157
	v_cvt_f32_ubyte3_e32 v181, v157
	v_fma_mixlo_f16 v179, v46, v32, 0
	v_fma_mixhi_f16 v179, v47, v181, 0
	v_add_u32_e32 v176, 0x100010, v176
	v_add_u32_e32 v177, 0x100010, v177
	v_add_u32_e32 v178, 0x100010, v178
	v_add_u32_e32 v179, 0x100010, v179
	v_and_b32_e32 v176, 0xffe0ffe0, v176
	v_and_b32_e32 v177, 0xffe0ffe0, v177
	v_and_b32_e32 v178, 0xffe0ffe0, v178
	v_and_b32_e32 v179, 0xffe0ffe0, v179
	v_add_co_u32_e32 v156, vcc, 0x48000, v134
	v_addc_co_u32_e32 v157, vcc, 0, v135, vcc
	global_store_dwordx4 v[156:157], v[176:179], off
	s_waitcnt vmcnt(15)
	v_pk_mul_f32 v[40:41], v[40:41], s[98:99] op_sel_hi:[1,0]
	v_pk_mul_f32 v[42:43], v[42:43], s[98:99] op_sel_hi:[1,0]
	v_pk_mul_f32 v[36:37], v[36:37], s[98:99] op_sel_hi:[1,0]
	v_pk_mul_f32 v[38:39], v[38:39], s[98:99] op_sel_hi:[1,0]
	v_cvt_f32_ubyte0_e32 v32, v158
	v_cvt_f32_ubyte1_e32 v181, v158
	v_fma_mixlo_f16 v190, v40, v32, 0
	v_fma_mixhi_f16 v190, v41, v181, 0
	v_cvt_f32_ubyte2_e32 v32, v158
	v_cvt_f32_ubyte3_e32 v181, v158
	v_fma_mixlo_f16 v191, v42, v32, 0
	v_fma_mixhi_f16 v191, v43, v181, 0
	v_cvt_f32_ubyte0_e32 v32, v159
	v_cvt_f32_ubyte1_e32 v181, v159
	v_fma_mixlo_f16 v192, v36, v32, 0
	v_fma_mixhi_f16 v192, v37, v181, 0
	v_cvt_f32_ubyte2_e32 v32, v159
	v_cvt_f32_ubyte3_e32 v181, v159
	v_fma_mixlo_f16 v193, v38, v32, 0
	v_fma_mixhi_f16 v193, v39, v181, 0
	v_add_u32_e32 v190, 0x100010, v190
	v_add_u32_e32 v191, 0x100010, v191
	v_add_u32_e32 v192, 0x100010, v192
	v_add_u32_e32 v193, 0x100010, v193
	v_and_b32_e32 v190, 0xffe0ffe0, v190
	v_and_b32_e32 v191, 0xffe0ffe0, v191
	v_and_b32_e32 v192, 0xffe0ffe0, v192
	v_and_b32_e32 v193, 0xffe0ffe0, v193
	v_add_co_u32_e32 v158, vcc, 0x48000, v134
	v_addc_co_u32_e32 v159, vcc, 0, v135, vcc
	global_store_dwordx4 v[158:159], v[190:193], off offset:256
	s_waitcnt vmcnt(15)
	v_pk_mul_f32 v[28:29], v[28:29], s[98:99] op_sel_hi:[1,0]
	v_pk_mul_f32 v[30:31], v[30:31], s[98:99] op_sel_hi:[1,0]
	v_pk_mul_f32 v[24:25], v[24:25], s[98:99] op_sel_hi:[1,0]
	v_pk_mul_f32 v[26:27], v[26:27], s[98:99] op_sel_hi:[1,0]
	v_cvt_f32_ubyte0_e32 v32, v160
	v_cvt_f32_ubyte1_e32 v181, v160
	v_fma_mixlo_f16 v198, v28, v32, 0
	v_fma_mixhi_f16 v198, v29, v181, 0
	v_cvt_f32_ubyte2_e32 v32, v160
	v_cvt_f32_ubyte3_e32 v181, v160
	v_fma_mixlo_f16 v199, v30, v32, 0
	v_fma_mixhi_f16 v199, v31, v181, 0
	v_cvt_f32_ubyte0_e32 v32, v161
	v_cvt_f32_ubyte1_e32 v181, v161
	v_fma_mixlo_f16 v200, v24, v32, 0
	v_fma_mixhi_f16 v200, v25, v181, 0
	v_cvt_f32_ubyte2_e32 v32, v161
	v_cvt_f32_ubyte3_e32 v181, v161
	v_fma_mixlo_f16 v201, v26, v32, 0
	v_fma_mixhi_f16 v201, v27, v181, 0
	v_add_u32_e32 v198, 0x100010, v198
	v_add_u32_e32 v199, 0x100010, v199
	v_add_u32_e32 v200, 0x100010, v200
	v_add_u32_e32 v201, 0x100010, v201
	v_and_b32_e32 v198, 0xffe0ffe0, v198
	v_and_b32_e32 v199, 0xffe0ffe0, v199
	v_and_b32_e32 v200, 0xffe0ffe0, v200
	v_and_b32_e32 v201, 0xffe0ffe0, v201
	v_add_co_u32_e32 v160, vcc, 0x50000, v134
	v_addc_co_u32_e32 v161, vcc, 0, v135, vcc
	global_store_dwordx4 v[160:161], v[198:201], off
	s_waitcnt vmcnt(15)
; template <unsigned D> __device__ __forceinline__ u32x4 rd8(u32x4 w) { w.x = rd<D>(w.x); w.y = rd<D>(w.y); w.z = rd<D>(w.z); w.w = rd<D>(w.w); return w; }
; __device__ __forceinline__ u32x4 pk8(const f32x4 v0, const f32x4 v1) { u32x4 w; w.x = pk_f16(v0[0], v0[1]); w.y = pk_f16(v0[2], v0[3]); w.z = pk_f16(v1[0], v1[1]); w.w = pk_f16(v1[2], v1[3]); return w; }
;     __device__ __forceinline__ void operator()(const f32x4 (&acc)[2][2][4][2], const GUnit& u, int wr, int wc, int fr, int fq, LAS unsigned char* lds) const {
;     ...
;                     for (int bj = 0; bj < 2; ++bj) { const size_t row = (size_t)(grow0 + ai * 128 + m * 16); const int col = gcol0 + bj * 128;
;                         gwv[m][bj] = *(const u32x2*)(sg + row * 2048 + col);
;                         pv[m][bj] = kind == K_Y2 ? *(const u32x4*)(mrg + row * 1024 + col) : (u32x4){0u, 0u, 0u, 0u}; }
;                 asm volatile("" ::: "memory");
; #pragma unroll
;                 for (int m = 0; m < 4; ++m)
; #pragma unroll
;                     for (int bj = 0; bj < 2; ++bj) { const size_t row = (size_t)(grow0 + ai * 128 + m * 16); const int col = gcol0 + bj * 128;
;                         const u32x2 gw = gwv[m][bj]; constexpr float q8 = 1.0f / 255.0f;
;                         const f32x4 g0 = {(float)(gw.x & 255u) * q8, (float)((gw.x >> 8) & 255u) * q8, (float)((gw.x >> 16) & 255u) * q8, (float)(gw.x >> 24) * q8};
;                         const f32x4 g1 = {(float)(gw.y & 255u) * q8, (float)((gw.y >> 8) & 255u) * q8, (float)((gw.y >> 16) & 255u) * q8, (float)(gw.y >> 24) * q8};
;                         f32x4 p0, p1; unpk8(pv[m][bj], p0, p1);
;                         *(u32x4*)(mrg + row * 1024 + col) = rd8<D_AMIX>(pk8(acc[ai][bj][m][0] * g0 + p0, acc[ai][bj][m][1] * g1 + p1)); }
;                 asm volatile("" ::: "memory"); }
	v_pk_mul_f32 v[20:21], v[20:21], s[98:99] op_sel_hi:[1,0]
	v_pk_mul_f32 v[22:23], v[22:23], s[98:99] op_sel_hi:[1,0]
	v_pk_mul_f32 v[16:17], v[16:17], s[98:99] op_sel_hi:[1,0]
	v_pk_mul_f32 v[18:19], v[18:19], s[98:99] op_sel_hi:[1,0]
	v_cvt_f32_ubyte0_e32 v32, v162
	v_cvt_f32_ubyte1_e32 v181, v162
	v_fma_mixlo_f16 v204, v20, v32, 0
	v_fma_mixhi_f16 v204, v21, v181, 0
	v_cvt_f32_ubyte2_e32 v32, v162
	v_cvt_f32_ubyte3_e32 v181, v162
	v_fma_mixlo_f16 v205, v22, v32, 0
	v_fma_mixhi_f16 v205, v23, v181, 0
	v_cvt_f32_ubyte0_e32 v32, v163
	v_cvt_f32_ubyte1_e32 v181, v163
	v_fma_mixlo_f16 v206, v16, v32, 0
	v_fma_mixhi_f16 v206, v17, v181, 0
	v_cvt_f32_ubyte2_e32 v32, v163
	v_cvt_f32_ubyte3_e32 v181, v163
	v_fma_mixlo_f16 v207, v18, v32, 0
	v_fma_mixhi_f16 v207, v19, v181, 0
	v_add_u32_e32 v204, 0x100010, v204
	v_add_u32_e32 v205, 0x100010, v205
	v_add_u32_e32 v206, 0x100010, v206
	v_add_u32_e32 v207, 0x100010, v207
	v_and_b32_e32 v204, 0xffe0ffe0, v204
	v_and_b32_e32 v205, 0xffe0ffe0, v205
	v_and_b32_e32 v206, 0xffe0ffe0, v206
	v_and_b32_e32 v207, 0xffe0ffe0, v207
	v_add_co_u32_e32 v162, vcc, 0x50000, v134
	v_addc_co_u32_e32 v163, vcc, 0, v135, vcc
	global_store_dwordx4 v[162:163], v[204:207], off offset:256
	s_waitcnt vmcnt(15)
	v_pk_mul_f32 v[12:13], v[12:13], s[98:99] op_sel_hi:[1,0]
	v_pk_mul_f32 v[14:15], v[14:15], s[98:99] op_sel_hi:[1,0]
	v_pk_mul_f32 v[8:9], v[8:9], s[98:99] op_sel_hi:[1,0]
	v_pk_mul_f32 v[10:11], v[10:11], s[98:99] op_sel_hi:[1,0]
	v_cvt_f32_ubyte0_e32 v32, v164
	v_cvt_f32_ubyte1_e32 v181, v164
	v_fma_mixlo_f16 v208, v12, v32, 0
	v_fma_mixhi_f16 v208, v13, v181, 0
	v_cvt_f32_ubyte2_e32 v32, v164
	v_cvt_f32_ubyte3_e32 v181, v164
	v_fma_mixlo_f16 v209, v14, v32, 0
	v_fma_mixhi_f16 v209, v15, v181, 0
	v_cvt_f32_ubyte0_e32 v32, v165
	v_cvt_f32_ubyte1_e32 v181, v165
	v_fma_mixlo_f16 v210, v8, v32, 0
	v_fma_mixhi_f16 v210, v9, v181, 0
	v_cvt_f32_ubyte2_e32 v32, v165
	v_cvt_f32_ubyte3_e32 v181, v165
	v_fma_mixlo_f16 v211, v10, v32, 0
	v_fma_mixhi_f16 v211, v11, v181, 0
	v_add_u32_e32 v208, 0x100010, v208
	v_add_u32_e32 v209, 0x100010, v209
	v_add_u32_e32 v210, 0x100010, v210
	v_add_u32_e32 v211, 0x100010, v211
	v_and_b32_e32 v208, 0xffe0ffe0, v208
	v_and_b32_e32 v209, 0xffe0ffe0, v209
	v_and_b32_e32 v210, 0xffe0ffe0, v210
	v_and_b32_e32 v211, 0xffe0ffe0, v211
	v_add_co_u32_e32 v164, vcc, 0x58000, v134
	v_addc_co_u32_e32 v165, vcc, 0, v135, vcc
	global_store_dwordx4 v[164:165], v[208:211], off
	s_waitcnt vmcnt(15)
	v_pk_mul_f32 v[4:5], v[4:5], s[98:99] op_sel_hi:[1,0]
	v_pk_mul_f32 v[6:7], v[6:7], s[98:99] op_sel_hi:[1,0]
	v_pk_mul_f32 v[0:1], v[0:1], s[98:99] op_sel_hi:[1,0]
	v_pk_mul_f32 v[2:3], v[2:3], s[98:99] op_sel_hi:[1,0]
	v_cvt_f32_ubyte0_e32 v32, v166
	v_cvt_f32_ubyte1_e32 v181, v166
	v_fma_mixlo_f16 v212, v4, v32, 0
	v_fma_mixhi_f16 v212, v5, v181, 0
	v_cvt_f32_ubyte2_e32 v32, v166
	v_cvt_f32_ubyte3_e32 v181, v166
	v_fma_mixlo_f16 v213, v6, v32, 0
	v_fma_mixhi_f16 v213, v7, v181, 0
	v_cvt_f32_ubyte0_e32 v32, v167
	v_cvt_f32_ubyte1_e32 v181, v167
	v_fma_mixlo_f16 v214, v0, v32, 0
	v_fma_mixhi_f16 v214, v1, v181, 0
	v_cvt_f32_ubyte2_e32 v32, v167
	v_cvt_f32_ubyte3_e32 v181, v167
	v_fma_mixlo_f16 v215, v2, v32, 0
	v_fma_mixhi_f16 v215, v3, v181, 0
	v_add_u32_e32 v212, 0x100010, v212
	v_add_u32_e32 v213, 0x100010, v213
	v_add_u32_e32 v214, 0x100010, v214
	v_add_u32_e32 v215, 0x100010, v215
	v_and_b32_e32 v212, 0xffe0ffe0, v212
	v_and_b32_e32 v213, 0xffe0ffe0, v213
	v_and_b32_e32 v214, 0xffe0ffe0, v214
	v_and_b32_e32 v215, 0xffe0ffe0, v215
	v_add_co_u32_e32 v166, vcc, 0x58000, v134
	v_addc_co_u32_e32 v167, vcc, 0, v135, vcc
	global_store_dwordx4 v[166:167], v[212:215], off offset:256
	s_branch .LBB0_300
.Ly_two:
	global_load_dwordx4 v[168:171], v[134:135], off
	global_load_dwordx4 v[172:175], v[134:135], off offset:256
	v_add_co_u32_e32 v194, vcc, 0x8000, v134
	v_addc_co_u32_e32 v195, vcc, 0, v135, vcc
	global_load_dwordx4 v[176:179], v[194:195], off
	global_load_dwordx4 v[190:193], v[194:195], off offset:256
	v_add_co_u32_e32 v194, vcc, 0x10000, v134
	v_addc_co_u32_e32 v195, vcc, 0, v135, vcc
	global_load_dwordx4 v[198:201], v[194:195], off
	global_load_dwordx4 v[204:207], v[194:195], off offset:256
	v_add_co_u32_e32 v194, vcc, 0x18000, v134
	v_addc_co_u32_e32 v195, vcc, 0, v135, vcc
	global_load_dwordx4 v[208:211], v[194:195], off
	global_load_dwordx4 v[212:215], v[194:195], off offset:256
	s_waitcnt vmcnt(7)
	v_pk_mul_f32 v[128:129], v[128:129], s[98:99] op_sel_hi:[1,0]
	v_pk_mul_f32 v[130:131], v[130:131], s[98:99] op_sel_hi:[1,0]
	v_pk_mul_f32 v[124:125], v[124:125], s[98:99] op_sel_hi:[1,0]
	v_pk_mul_f32 v[126:127], v[126:127], s[98:99] op_sel_hi:[1,0]
	v_cvt_f32_ubyte0_e32 v32, v136
	v_cvt_f32_ubyte1_e32 v181, v136
	v_fma_mixlo_f16 v168, v128, v32, v168 op_sel_hi:[0,0,1]
	v_fma_mixhi_f16 v168, v129, v181, v168 op_sel:[0,0,1] op_sel_hi:[0,0,1]
	v_cvt_f32_ubyte2_e32 v32, v136
	v_cvt_f32_ubyte3_e32 v181, v136
	v_fma_mixlo_f16 v169, v130, v32, v169 op_sel_hi:[0,0,1]
	v_fma_mixhi_f16 v169, v131, v181, v169 op_sel:[0,0,1] op_sel_hi:[0,0,1]
	v_cvt_f32_ubyte0_e32 v32, v137
	v_cvt_f32_ubyte1_e32 v181, v137
	v_fma_mixlo_f16 v170, v124, v32, v170 op_sel_hi:[0,0,1]
	v_fma_mixhi_f16 v170, v125, v181, v170 op_sel:[0,0,1] op_sel_hi:[0,0,1]
	v_cvt_f32_ubyte2_e32 v32, v137
	v_cvt_f32_ubyte3_e32 v181, v137
	v_fma_mixlo_f16 v171, v126, v32, v171 op_sel_hi:[0,0,1]
	v_fma_mixhi_f16 v171, v127, v181, v171 op_sel:[0,0,1] op_sel_hi:[0,0,1]
	v_add_u32_e32 v168, 0x100010, v168
	v_add_u32_e32 v169, 0x100010, v169
	v_add_u32_e32 v170, 0x100010, v170
	v_add_u32_e32 v171, 0x100010, v171
	v_and_b32_e32 v168, 0xffe0ffe0, v168
	v_and_b32_e32 v169, 0xffe0ffe0, v169
	v_and_b32_e32 v170, 0xffe0ffe0, v170
	v_and_b32_e32 v171, 0xffe0ffe0, v171
	global_store_dwordx4 v[134:135], v[168:171], off
	v_add_co_u32_e32 v136, vcc, 0x40000, v134
	v_addc_co_u32_e32 v137, vcc, 0, v135, vcc
	global_load_dwordx4 v[168:171], v[136:137], off
	s_waitcnt vmcnt(8)
; template <unsigned D> __device__ __forceinline__ u32x4 rd8(u32x4 w) { w.x = rd<D>(w.x); w.y = rd<D>(w.y); w.z = rd<D>(w.z); w.w = rd<D>(w.w); return w; }
; __device__ __forceinline__ u32x4 pk8(const f32x4 v0, const f32x4 v1) { u32x4 w; w.x = pk_f16(v0[0], v0[1]); w.y = pk_f16(v0[2], v0[3]); w.z = pk_f16(v1[0], v1[1]); w.w = pk_f16(v1[2], v1[3]); return w; }
;     __device__ __forceinline__ void operator()(const f32x4 (&acc)[2][2][4][2], const GUnit& u, int wr, int wc, int fr, int fq, LAS unsigned char* lds) const {
;     ...
;                     for (int bj = 0; bj < 2; ++bj) { const size_t row = (size_t)(grow0 + ai * 128 + m * 16); const int col = gcol0 + bj * 128;
;                         gwv[m][bj] = *(const u32x2*)(sg + row * 2048 + col);
;                         pv[m][bj] = kind == K_Y2 ? *(const u32x4*)(mrg + row * 1024 + col) : (u32x4){0u, 0u, 0u, 0u}; }
;                 asm volatile("" ::: "memory");
; #pragma unroll
;                 for (int m = 0; m < 4; ++m)
; #pragma unroll
;                     for (int bj = 0; bj < 2; ++bj) { const size_t row = (size_t)(grow0 + ai * 128 + m * 16); const int col = gcol0 + bj * 128;
;                         const u32x2 gw = gwv[m][bj]; constexpr float q8 = 1.0f / 255.0f;
;                         const f32x4 g0 = {(float)(gw.x & 255u) * q8, (float)((gw.x >> 8) & 255u) * q8, (float)((gw.x >> 16) & 255u) * q8, (float)(gw.x >> 24) * q8};
;                         const f32x4 g1 = {(float)(gw.y & 255u) * q8, (float)((gw.y >> 8) & 255u) * q8, (float)((gw.y >> 16) & 255u) * q8, (float)(gw.y >> 24) * q8};
;                         f32x4 p0, p1; unpk8(pv[m][bj], p0, p1);
;                         *(u32x4*)(mrg + row * 1024 + col) = rd8<D_AMIX>(pk8(acc[ai][bj][m][0] * g0 + p0, acc[ai][bj][m][1] * g1 + p1)); }
;                 asm volatile("" ::: "memory"); }
	v_pk_mul_f32 v[120:121], v[120:121], s[98:99] op_sel_hi:[1,0]
	v_pk_mul_f32 v[122:123], v[122:123], s[98:99] op_sel_hi:[1,0]
	v_pk_mul_f32 v[116:117], v[116:117], s[98:99] op_sel_hi:[1,0]
	v_pk_mul_f32 v[118:119], v[118:119], s[98:99] op_sel_hi:[1,0]
	v_cvt_f32_ubyte0_e32 v32, v138
	v_cvt_f32_ubyte1_e32 v181, v138
	v_fma_mixlo_f16 v172, v120, v32, v172 op_sel_hi:[0,0,1]
	v_fma_mixhi_f16 v172, v121, v181, v172 op_sel:[0,0,1] op_sel_hi:[0,0,1]
	v_cvt_f32_ubyte2_e32 v32, v138
	v_cvt_f32_ubyte3_e32 v181, v138
	v_fma_mixlo_f16 v173, v122, v32, v173 op_sel_hi:[0,0,1]
	v_fma_mixhi_f16 v173, v123, v181, v173 op_sel:[0,0,1] op_sel_hi:[0,0,1]
	v_cvt_f32_ubyte0_e32 v32, v139
	v_cvt_f32_ubyte1_e32 v181, v139
	v_fma_mixlo_f16 v174, v116, v32, v174 op_sel_hi:[0,0,1]
	v_fma_mixhi_f16 v174, v117, v181, v174 op_sel:[0,0,1] op_sel_hi:[0,0,1]
	v_cvt_f32_ubyte2_e32 v32, v139
	v_cvt_f32_ubyte3_e32 v181, v139
	v_fma_mixlo_f16 v175, v118, v32, v175 op_sel_hi:[0,0,1]
	v_fma_mixhi_f16 v175, v119, v181, v175 op_sel:[0,0,1] op_sel_hi:[0,0,1]
	v_add_u32_e32 v172, 0x100010, v172
	v_add_u32_e32 v173, 0x100010, v173
	v_add_u32_e32 v174, 0x100010, v174
	v_add_u32_e32 v175, 0x100010, v175
	v_and_b32_e32 v172, 0xffe0ffe0, v172
	v_and_b32_e32 v173, 0xffe0ffe0, v173
	v_and_b32_e32 v174, 0xffe0ffe0, v174
	v_and_b32_e32 v175, 0xffe0ffe0, v175
	global_store_dwordx4 v[134:135], v[172:175], off offset:256
	v_add_co_u32_e32 v138, vcc, 0x40000, v134
	v_addc_co_u32_e32 v139, vcc, 0, v135, vcc
	global_load_dwordx4 v[172:175], v[138:139], off offset:256
	s_waitcnt vmcnt(9)
	v_pk_mul_f32 v[112:113], v[112:113], s[98:99] op_sel_hi:[1,0]
	v_pk_mul_f32 v[114:115], v[114:115], s[98:99] op_sel_hi:[1,0]
	v_pk_mul_f32 v[108:109], v[108:109], s[98:99] op_sel_hi:[1,0]
	v_pk_mul_f32 v[110:111], v[110:111], s[98:99] op_sel_hi:[1,0]
	v_cvt_f32_ubyte0_e32 v32, v140
	v_cvt_f32_ubyte1_e32 v181, v140
	v_fma_mixlo_f16 v176, v112, v32, v176 op_sel_hi:[0,0,1]
	v_fma_mixhi_f16 v176, v113, v181, v176 op_sel:[0,0,1] op_sel_hi:[0,0,1]
	v_cvt_f32_ubyte2_e32 v32, v140
	v_cvt_f32_ubyte3_e32 v181, v140
	v_fma_mixlo_f16 v177, v114, v32, v177 op_sel_hi:[0,0,1]
	v_fma_mixhi_f16 v177, v115, v181, v177 op_sel:[0,0,1] op_sel_hi:[0,0,1]
	v_cvt_f32_ubyte0_e32 v32, v141
	v_cvt_f32_ubyte1_e32 v181, v141
	v_fma_mixlo_f16 v178, v108, v32, v178 op_sel_hi:[0,0,1]
	v_fma_mixhi_f16 v178, v109, v181, v178 op_sel:[0,0,1] op_sel_hi:[0,0,1]
	v_cvt_f32_ubyte2_e32 v32, v141
	v_cvt_f32_ubyte3_e32 v181, v141
	v_fma_mixlo_f16 v179, v110, v32, v179 op_sel_hi:[0,0,1]
	v_fma_mixhi_f16 v179, v111, v181, v179 op_sel:[0,0,1] op_sel_hi:[0,0,1]
	v_add_u32_e32 v176, 0x100010, v176
	v_add_u32_e32 v177, 0x100010, v177
	v_add_u32_e32 v178, 0x100010, v178
	v_add_u32_e32 v179, 0x100010, v179
	v_and_b32_e32 v176, 0xffe0ffe0, v176
	v_and_b32_e32 v177, 0xffe0ffe0, v177
	v_and_b32_e32 v178, 0xffe0ffe0, v178
	v_and_b32_e32 v179, 0xffe0ffe0, v179
	v_add_co_u32_e32 v140, vcc, 0x8000, v134
	v_addc_co_u32_e32 v141, vcc, 0, v135, vcc
	global_store_dwordx4 v[140:141], v[176:179], off
	v_add_co_u32_e32 v140, vcc, 0x40000, v140
	v_addc_co_u32_e32 v141, vcc, 0, v141, vcc
	global_load_dwordx4 v[176:179], v[140:141], off
	s_waitcnt vmcnt(10)
	v_pk_mul_f32 v[104:105], v[104:105], s[98:99] op_sel_hi:[1,0]
	v_pk_mul_f32 v[106:107], v[106:107], s[98:99] op_sel_hi:[1,0]
	v_pk_mul_f32 v[100:101], v[100:101], s[98:99] op_sel_hi:[1,0]
	v_pk_mul_f32 v[102:103], v[102:103], s[98:99] op_sel_hi:[1,0]
	v_cvt_f32_ubyte0_e32 v32, v142
	v_cvt_f32_ubyte1_e32 v181, v142
	v_fma_mixlo_f16 v190, v104, v32, v190 op_sel_hi:[0,0,1]
	v_fma_mixhi_f16 v190, v105, v181, v190 op_sel:[0,0,1] op_sel_hi:[0,0,1]
	v_cvt_f32_ubyte2_e32 v32, v142
	v_cvt_f32_ubyte3_e32 v181, v142
	v_fma_mixlo_f16 v191, v106, v32, v191 op_sel_hi:[0,0,1]
	v_fma_mixhi_f16 v191, v107, v181, v191 op_sel:[0,0,1] op_sel_hi:[0,0,1]
	v_cvt_f32_ubyte0_e32 v32, v143
	v_cvt_f32_ubyte1_e32 v181, v143
	v_fma_mixlo_f16 v192, v100, v32, v192 op_sel_hi:[0,0,1]
	v_fma_mixhi_f16 v192, v101, v181, v192 op_sel:[0,0,1] op_sel_hi:[0,0,1]
	v_cvt_f32_ubyte2_e32 v32, v143
	v_cvt_f32_ubyte3_e32 v181, v143
	v_fma_mixlo_f16 v193, v102, v32, v193 op_sel_hi:[0,0,1]
	v_fma_mixhi_f16 v193, v103, v181, v193 op_sel:[0,0,1] op_sel_hi:[0,0,1]
	v_add_u32_e32 v190, 0x100010, v190
	v_add_u32_e32 v191, 0x100010, v191
	v_add_u32_e32 v192, 0x100010, v192
	v_add_u32_e32 v193, 0x100010, v193
	v_and_b32_e32 v190, 0xffe0ffe0, v190
	v_and_b32_e32 v191, 0xffe0ffe0, v191
	v_and_b32_e32 v192, 0xffe0ffe0, v192
	v_and_b32_e32 v193, 0xffe0ffe0, v193
	v_add_co_u32_e32 v142, vcc, 0x8000, v134
	v_addc_co_u32_e32 v143, vcc, 0, v135, vcc
	global_store_dwordx4 v[142:143], v[190:193], off offset:256
	v_add_co_u32_e32 v142, vcc, 0x40000, v142
	v_addc_co_u32_e32 v143, vcc, 0, v143, vcc
	global_load_dwordx4 v[190:193], v[142:143], off offset:256
	s_waitcnt vmcnt(11)
	v_pk_mul_f32 v[96:97], v[96:97], s[98:99] op_sel_hi:[1,0]
	v_pk_mul_f32 v[98:99], v[98:99], s[98:99] op_sel_hi:[1,0]
	v_pk_mul_f32 v[92:93], v[92:93], s[98:99] op_sel_hi:[1,0]
	v_pk_mul_f32 v[94:95], v[94:95], s[98:99] op_sel_hi:[1,0]
	v_cvt_f32_ubyte0_e32 v32, v144
	v_cvt_f32_ubyte1_e32 v181, v144
	v_fma_mixlo_f16 v198, v96, v32, v198 op_sel_hi:[0,0,1]
	v_fma_mixhi_f16 v198, v97, v181, v198 op_sel:[0,0,1] op_sel_hi:[0,0,1]
	v_cvt_f32_ubyte2_e32 v32, v144
	v_cvt_f32_ubyte3_e32 v181, v144
	v_fma_mixlo_f16 v199, v98, v32, v199 op_sel_hi:[0,0,1]
	v_fma_mixhi_f16 v199, v99, v181, v199 op_sel:[0,0,1] op_sel_hi:[0,0,1]
	v_cvt_f32_ubyte0_e32 v32, v145
	v_cvt_f32_ubyte1_e32 v181, v145
	v_fma_mixlo_f16 v200, v92, v32, v200 op_sel_hi:[0,0,1]
	v_fma_mixhi_f16 v200, v93, v181, v200 op_sel:[0,0,1] op_sel_hi:[0,0,1]
	v_cvt_f32_ubyte2_e32 v32, v145
	v_cvt_f32_ubyte3_e32 v181, v145
	v_fma_mixlo_f16 v201, v94, v32, v201 op_sel_hi:[0,0,1]
	v_fma_mixhi_f16 v201, v95, v181, v201 op_sel:[0,0,1] op_sel_hi:[0,0,1]
	v_add_u32_e32 v198, 0x100010, v198
	v_add_u32_e32 v199, 0x100010, v199
	v_add_u32_e32 v200, 0x100010, v200
	v_add_u32_e32 v201, 0x100010, v201
	v_and_b32_e32 v198, 0xffe0ffe0, v198
	v_and_b32_e32 v199, 0xffe0ffe0, v199
	v_and_b32_e32 v200, 0xffe0ffe0, v200
	v_and_b32_e32 v201, 0xffe0ffe0, v201
	v_add_co_u32_e32 v144, vcc, 0x10000, v134
	v_addc_co_u32_e32 v145, vcc, 0, v135, vcc
	global_store_dwordx4 v[144:145], v[198:201], off
	v_add_co_u32_e32 v144, vcc, 0x40000, v144
	v_addc_co_u32_e32 v145, vcc, 0, v145, vcc
	global_load_dwordx4 v[198:201], v[144:145], off
	s_waitcnt vmcnt(12)
; template <unsigned D> __device__ __forceinline__ u32x4 rd8(u32x4 w) { w.x = rd<D>(w.x); w.y = rd<D>(w.y); w.z = rd<D>(w.z); w.w = rd<D>(w.w); return w; }
; __device__ __forceinline__ u32x4 pk8(const f32x4 v0, const f32x4 v1) { u32x4 w; w.x = pk_f16(v0[0], v0[1]); w.y = pk_f16(v0[2], v0[3]); w.z = pk_f16(v1[0], v1[1]); w.w = pk_f16(v1[2], v1[3]); return w; }
;     __device__ __forceinline__ void operator()(const f32x4 (&acc)[2][2][4][2], const GUnit& u, int wr, int wc, int fr, int fq, LAS unsigned char* lds) const {
;     ...
;                     for (int bj = 0; bj < 2; ++bj) { const size_t row = (size_t)(grow0 + ai * 128 + m * 16); const int col = gcol0 + bj * 128;
;                         gwv[m][bj] = *(const u32x2*)(sg + row * 2048 + col);
;                         pv[m][bj] = kind == K_Y2 ? *(const u32x4*)(mrg + row * 1024 + col) : (u32x4){0u, 0u, 0u, 0u}; }
;                 asm volatile("" ::: "memory");
; #pragma unroll
;                 for (int m = 0; m < 4; ++m)
; #pragma unroll
;                     for (int bj = 0; bj < 2; ++bj) { const size_t row = (size_t)(grow0 + ai * 128 + m * 16); const int col = gcol0 + bj * 128;
;                         const u32x2 gw = gwv[m][bj]; constexpr float q8 = 1.0f / 255.0f;
;                         const f32x4 g0 = {(float)(gw.x & 255u) * q8, (float)((gw.x >> 8) & 255u) * q8, (float)((gw.x >> 16) & 255u) * q8, (float)(gw.x >> 24) * q8};
;                         const f32x4 g1 = {(float)(gw.y & 255u) * q8, (float)((gw.y >> 8) & 255u) * q8, (float)((gw.y >> 16) & 255u) * q8, (float)(gw.y >> 24) * q8};
;                         f32x4 p0, p1; unpk8(pv[m][bj], p0, p1);
;                         *(u32x4*)(mrg + row * 1024 + col) = rd8<D_AMIX>(pk8(acc[ai][bj][m][0] * g0 + p0, acc[ai][bj][m][1] * g1 + p1)); }
;                 asm volatile("" ::: "memory"); }
	v_pk_mul_f32 v[88:89], v[88:89], s[98:99] op_sel_hi:[1,0]
	v_pk_mul_f32 v[90:91], v[90:91], s[98:99] op_sel_hi:[1,0]
	v_pk_mul_f32 v[84:85], v[84:85], s[98:99] op_sel_hi:[1,0]
	v_pk_mul_f32 v[86:87], v[86:87], s[98:99] op_sel_hi:[1,0]
	v_cvt_f32_ubyte0_e32 v32, v146
	v_cvt_f32_ubyte1_e32 v181, v146
	v_fma_mixlo_f16 v204, v88, v32, v204 op_sel_hi:[0,0,1]
	v_fma_mixhi_f16 v204, v89, v181, v204 op_sel:[0,0,1] op_sel_hi:[0,0,1]
	v_cvt_f32_ubyte2_e32 v32, v146
	v_cvt_f32_ubyte3_e32 v181, v146
	v_fma_mixlo_f16 v205, v90, v32, v205 op_sel_hi:[0,0,1]
	v_fma_mixhi_f16 v205, v91, v181, v205 op_sel:[0,0,1] op_sel_hi:[0,0,1]
	v_cvt_f32_ubyte0_e32 v32, v147
	v_cvt_f32_ubyte1_e32 v181, v147
	v_fma_mixlo_f16 v206, v84, v32, v206 op_sel_hi:[0,0,1]
	v_fma_mixhi_f16 v206, v85, v181, v206 op_sel:[0,0,1] op_sel_hi:[0,0,1]
	v_cvt_f32_ubyte2_e32 v32, v147
	v_cvt_f32_ubyte3_e32 v181, v147
	v_fma_mixlo_f16 v207, v86, v32, v207 op_sel_hi:[0,0,1]
	v_fma_mixhi_f16 v207, v87, v181, v207 op_sel:[0,0,1] op_sel_hi:[0,0,1]
	v_add_u32_e32 v204, 0x100010, v204
	v_add_u32_e32 v205, 0x100010, v205
	v_add_u32_e32 v206, 0x100010, v206
	v_add_u32_e32 v207, 0x100010, v207
	v_and_b32_e32 v204, 0xffe0ffe0, v204
	v_and_b32_e32 v205, 0xffe0ffe0, v205
	v_and_b32_e32 v206, 0xffe0ffe0, v206
	v_and_b32_e32 v207, 0xffe0ffe0, v207
	v_add_co_u32_e32 v146, vcc, 0x10000, v134
	v_addc_co_u32_e32 v147, vcc, 0, v135, vcc
	global_store_dwordx4 v[146:147], v[204:207], off offset:256
	v_add_co_u32_e32 v146, vcc, 0x40000, v146
	v_addc_co_u32_e32 v147, vcc, 0, v147, vcc
	global_load_dwordx4 v[204:207], v[146:147], off offset:256
	s_waitcnt vmcnt(13)
	v_pk_mul_f32 v[80:81], v[80:81], s[98:99] op_sel_hi:[1,0]
	v_pk_mul_f32 v[82:83], v[82:83], s[98:99] op_sel_hi:[1,0]
	v_pk_mul_f32 v[76:77], v[76:77], s[98:99] op_sel_hi:[1,0]
	v_pk_mul_f32 v[78:79], v[78:79], s[98:99] op_sel_hi:[1,0]
	v_cvt_f32_ubyte0_e32 v32, v148
	v_cvt_f32_ubyte1_e32 v181, v148
	v_fma_mixlo_f16 v208, v80, v32, v208 op_sel_hi:[0,0,1]
	v_fma_mixhi_f16 v208, v81, v181, v208 op_sel:[0,0,1] op_sel_hi:[0,0,1]
	v_cvt_f32_ubyte2_e32 v32, v148
	v_cvt_f32_ubyte3_e32 v181, v148
	v_fma_mixlo_f16 v209, v82, v32, v209 op_sel_hi:[0,0,1]
	v_fma_mixhi_f16 v209, v83, v181, v209 op_sel:[0,0,1] op_sel_hi:[0,0,1]
	v_cvt_f32_ubyte0_e32 v32, v149
	v_cvt_f32_ubyte1_e32 v181, v149
	v_fma_mixlo_f16 v210, v76, v32, v210 op_sel_hi:[0,0,1]
	v_fma_mixhi_f16 v210, v77, v181, v210 op_sel:[0,0,1] op_sel_hi:[0,0,1]
	v_cvt_f32_ubyte2_e32 v32, v149
	v_cvt_f32_ubyte3_e32 v181, v149
	v_fma_mixlo_f16 v211, v78, v32, v211 op_sel_hi:[0,0,1]
	v_fma_mixhi_f16 v211, v79, v181, v211 op_sel:[0,0,1] op_sel_hi:[0,0,1]
	v_add_u32_e32 v208, 0x100010, v208
	v_add_u32_e32 v209, 0x100010, v209
	v_add_u32_e32 v210, 0x100010, v210
	v_add_u32_e32 v211, 0x100010, v211
	v_and_b32_e32 v208, 0xffe0ffe0, v208
	v_and_b32_e32 v209, 0xffe0ffe0, v209
	v_and_b32_e32 v210, 0xffe0ffe0, v210
	v_and_b32_e32 v211, 0xffe0ffe0, v211
	v_add_co_u32_e32 v148, vcc, 0x18000, v134
	v_addc_co_u32_e32 v149, vcc, 0, v135, vcc
	global_store_dwordx4 v[148:149], v[208:211], off
	v_add_co_u32_e32 v148, vcc, 0x40000, v148
	v_addc_co_u32_e32 v149, vcc, 0, v149, vcc
	global_load_dwordx4 v[208:211], v[148:149], off
	s_waitcnt vmcnt(14)
	v_pk_mul_f32 v[72:73], v[72:73], s[98:99] op_sel_hi:[1,0]
	v_pk_mul_f32 v[74:75], v[74:75], s[98:99] op_sel_hi:[1,0]
	v_pk_mul_f32 v[68:69], v[68:69], s[98:99] op_sel_hi:[1,0]
	v_pk_mul_f32 v[70:71], v[70:71], s[98:99] op_sel_hi:[1,0]
	v_cvt_f32_ubyte0_e32 v32, v150
	v_cvt_f32_ubyte1_e32 v181, v150
	v_fma_mixlo_f16 v212, v72, v32, v212 op_sel_hi:[0,0,1]
	v_fma_mixhi_f16 v212, v73, v181, v212 op_sel:[0,0,1] op_sel_hi:[0,0,1]
	v_cvt_f32_ubyte2_e32 v32, v150
	v_cvt_f32_ubyte3_e32 v181, v150
	v_fma_mixlo_f16 v213, v74, v32, v213 op_sel_hi:[0,0,1]
	v_fma_mixhi_f16 v213, v75, v181, v213 op_sel:[0,0,1] op_sel_hi:[0,0,1]
	v_cvt_f32_ubyte0_e32 v32, v151
	v_cvt_f32_ubyte1_e32 v181, v151
	v_fma_mixlo_f16 v214, v68, v32, v214 op_sel_hi:[0,0,1]
	v_fma_mixhi_f16 v214, v69, v181, v214 op_sel:[0,0,1] op_sel_hi:[0,0,1]
	v_cvt_f32_ubyte2_e32 v32, v151
	v_cvt_f32_ubyte3_e32 v181, v151
	v_fma_mixlo_f16 v215, v70, v32, v215 op_sel_hi:[0,0,1]
	v_fma_mixhi_f16 v215, v71, v181, v215 op_sel:[0,0,1] op_sel_hi:[0,0,1]
	v_add_u32_e32 v212, 0x100010, v212
	v_add_u32_e32 v213, 0x100010, v213
	v_add_u32_e32 v214, 0x100010, v214
	v_add_u32_e32 v215, 0x100010, v215
	v_and_b32_e32 v212, 0xffe0ffe0, v212
	v_and_b32_e32 v213, 0xffe0ffe0, v213
	v_and_b32_e32 v214, 0xffe0ffe0, v214
	v_and_b32_e32 v215, 0xffe0ffe0, v215
	v_add_co_u32_e32 v150, vcc, 0x18000, v134
	v_addc_co_u32_e32 v151, vcc, 0, v135, vcc
	global_store_dwordx4 v[150:151], v[212:215], off offset:256
	v_add_co_u32_e32 v150, vcc, 0x40000, v150
	v_addc_co_u32_e32 v151, vcc, 0, v151, vcc
	global_load_dwordx4 v[212:215], v[150:151], off offset:256
	s_waitcnt vmcnt(14)
	v_pk_mul_f32 v[64:65], v[64:65], s[98:99] op_sel_hi:[1,0]
	v_pk_mul_f32 v[66:67], v[66:67], s[98:99] op_sel_hi:[1,0]
	v_pk_mul_f32 v[60:61], v[60:61], s[98:99] op_sel_hi:[1,0]
	v_pk_mul_f32 v[62:63], v[62:63], s[98:99] op_sel_hi:[1,0]
	v_cvt_f32_ubyte0_e32 v32, v152
	v_cvt_f32_ubyte1_e32 v181, v152
	v_fma_mixlo_f16 v168, v64, v32, v168 op_sel_hi:[0,0,1]
	v_fma_mixhi_f16 v168, v65, v181, v168 op_sel:[0,0,1] op_sel_hi:[0,0,1]
	v_cvt_f32_ubyte2_e32 v32, v152
	v_cvt_f32_ubyte3_e32 v181, v152
	v_fma_mixlo_f16 v169, v66, v32, v169 op_sel_hi:[0,0,1]
	v_fma_mixhi_f16 v169, v67, v181, v169 op_sel:[0,0,1] op_sel_hi:[0,0,1]
	v_cvt_f32_ubyte0_e32 v32, v153
	v_cvt_f32_ubyte1_e32 v181, v153
	v_fma_mixlo_f16 v170, v60, v32, v170 op_sel_hi:[0,0,1]
	v_fma_mixhi_f16 v170, v61, v181, v170 op_sel:[0,0,1] op_sel_hi:[0,0,1]
	v_cvt_f32_ubyte2_e32 v32, v153
	v_cvt_f32_ubyte3_e32 v181, v153
	v_fma_mixlo_f16 v171, v62, v32, v171 op_sel_hi:[0,0,1]
	v_fma_mixhi_f16 v171, v63, v181, v171 op_sel:[0,0,1] op_sel_hi:[0,0,1]
	v_add_u32_e32 v168, 0x100010, v168
	v_add_u32_e32 v169, 0x100010, v169
	v_add_u32_e32 v170, 0x100010, v170
	v_add_u32_e32 v171, 0x100010, v171
	v_and_b32_e32 v168, 0xffe0ffe0, v168
	v_and_b32_e32 v169, 0xffe0ffe0, v169
	v_and_b32_e32 v170, 0xffe0ffe0, v170
	v_and_b32_e32 v171, 0xffe0ffe0, v171
	v_add_co_u32_e32 v152, vcc, 0x40000, v134
	v_addc_co_u32_e32 v153, vcc, 0, v135, vcc
	global_store_dwordx4 v[152:153], v[168:171], off
	s_waitcnt vmcnt(13)
; template <unsigned D> __device__ __forceinline__ u32x4 rd8(u32x4 w) { w.x = rd<D>(w.x); w.y = rd<D>(w.y); w.z = rd<D>(w.z); w.w = rd<D>(w.w); return w; }
; __device__ __forceinline__ u32x4 pk8(const f32x4 v0, const f32x4 v1) { u32x4 w; w.x = pk_f16(v0[0], v0[1]); w.y = pk_f16(v0[2], v0[3]); w.z = pk_f16(v1[0], v1[1]); w.w = pk_f16(v1[2], v1[3]); return w; }
;     __device__ __forceinline__ void operator()(const f32x4 (&acc)[2][2][4][2], const GUnit& u, int wr, int wc, int fr, int fq, LAS unsigned char* lds) const {
;     ...
;                     for (int bj = 0; bj < 2; ++bj) { const size_t row = (size_t)(grow0 + ai * 128 + m * 16); const int col = gcol0 + bj * 128;
;                         gwv[m][bj] = *(const u32x2*)(sg + row * 2048 + col);
;                         pv[m][bj] = kind == K_Y2 ? *(const u32x4*)(mrg + row * 1024 + col) : (u32x4){0u, 0u, 0u, 0u}; }
;                 asm volatile("" ::: "memory");
; #pragma unroll
;                 for (int m = 0; m < 4; ++m)
; #pragma unroll
;                     for (int bj = 0; bj < 2; ++bj) { const size_t row = (size_t)(grow0 + ai * 128 + m * 16); const int col = gcol0 + bj * 128;
;                         const u32x2 gw = gwv[m][bj]; constexpr float q8 = 1.0f / 255.0f;
;                         const f32x4 g0 = {(float)(gw.x & 255u) * q8, (float)((gw.x >> 8) & 255u) * q8, (float)((gw.x >> 16) & 255u) * q8, (float)(gw.x >> 24) * q8};
;                         const f32x4 g1 = {(float)(gw.y & 255u) * q8, (float)((gw.y >> 8) & 255u) * q8, (float)((gw.y >> 16) & 255u) * q8, (float)(gw.y >> 24) * q8};
;                         f32x4 p0, p1; unpk8(pv[m][bj], p0, p1);
;                         *(u32x4*)(mrg + row * 1024 + col) = rd8<D_AMIX>(pk8(acc[ai][bj][m][0] * g0 + p0, acc[ai][bj][m][1] * g1 + p1)); }
;                 asm volatile("" ::: "memory"); }
	v_pk_mul_f32 v[56:57], v[56:57], s[98:99] op_sel_hi:[1,0]
	v_pk_mul_f32 v[58:59], v[58:59], s[98:99] op_sel_hi:[1,0]
	v_pk_mul_f32 v[52:53], v[52:53], s[98:99] op_sel_hi:[1,0]
	v_pk_mul_f32 v[54:55], v[54:55], s[98:99] op_sel_hi:[1,0]
	v_cvt_f32_ubyte0_e32 v32, v154
	v_cvt_f32_ubyte1_e32 v181, v154
	v_fma_mixlo_f16 v172, v56, v32, v172 op_sel_hi:[0,0,1]
	v_fma_mixhi_f16 v172, v57, v181, v172 op_sel:[0,0,1] op_sel_hi:[0,0,1]
	v_cvt_f32_ubyte2_e32 v32, v154
	v_cvt_f32_ubyte3_e32 v181, v154
	v_fma_mixlo_f16 v173, v58, v32, v173 op_sel_hi:[0,0,1]
	v_fma_mixhi_f16 v173, v59, v181, v173 op_sel:[0,0,1] op_sel_hi:[0,0,1]
	v_cvt_f32_ubyte0_e32 v32, v155
	v_cvt_f32_ubyte1_e32 v181, v155
	v_fma_mixlo_f16 v174, v52, v32, v174 op_sel_hi:[0,0,1]
	v_fma_mixhi_f16 v174, v53, v181, v174 op_sel:[0,0,1] op_sel_hi:[0,0,1]
	v_cvt_f32_ubyte2_e32 v32, v155
	v_cvt_f32_ubyte3_e32 v181, v155
	v_fma_mixlo_f16 v175, v54, v32, v175 op_sel_hi:[0,0,1]
	v_fma_mixhi_f16 v175, v55, v181, v175 op_sel:[0,0,1] op_sel_hi:[0,0,1]
	v_add_u32_e32 v172, 0x100010, v172
	v_add_u32_e32 v173, 0x100010, v173
	v_add_u32_e32 v174, 0x100010, v174
	v_add_u32_e32 v175, 0x100010, v175
	v_and_b32_e32 v172, 0xffe0ffe0, v172
	v_and_b32_e32 v173, 0xffe0ffe0, v173
	v_and_b32_e32 v174, 0xffe0ffe0, v174
	v_and_b32_e32 v175, 0xffe0ffe0, v175
	v_add_co_u32_e32 v154, vcc, 0x40000, v134
	v_addc_co_u32_e32 v155, vcc, 0, v135, vcc
	global_store_dwordx4 v[154:155], v[172:175], off offset:256
	s_waitcnt vmcnt(12)
	v_pk_mul_f32 v[48:49], v[48:49], s[98:99] op_sel_hi:[1,0]
	v_pk_mul_f32 v[50:51], v[50:51], s[98:99] op_sel_hi:[1,0]
	v_pk_mul_f32 v[44:45], v[44:45], s[98:99] op_sel_hi:[1,0]
	v_pk_mul_f32 v[46:47], v[46:47], s[98:99] op_sel_hi:[1,0]
	v_cvt_f32_ubyte0_e32 v32, v156
	v_cvt_f32_ubyte1_e32 v181, v156
	v_fma_mixlo_f16 v176, v48, v32, v176 op_sel_hi:[0,0,1]
	v_fma_mixhi_f16 v176, v49, v181, v176 op_sel:[0,0,1] op_sel_hi:[0,0,1]
	v_cvt_f32_ubyte2_e32 v32, v156
	v_cvt_f32_ubyte3_e32 v181, v156
	v_fma_mixlo_f16 v177, v50, v32, v177 op_sel_hi:[0,0,1]
	v_fma_mixhi_f16 v177, v51, v181, v177 op_sel:[0,0,1] op_sel_hi:[0,0,1]
	v_cvt_f32_ubyte0_e32 v32, v157
	v_cvt_f32_ubyte1_e32 v181, v157
	v_fma_mixlo_f16 v178, v44, v32, v178 op_sel_hi:[0,0,1]
	v_fma_mixhi_f16 v178, v45, v181, v178 op_sel:[0,0,1] op_sel_hi:[0,0,1]
	v_cvt_f32_ubyte2_e32 v32, v157
	v_cvt_f32_ubyte3_e32 v181, v157
	v_fma_mixlo_f16 v179, v46, v32, v179 op_sel_hi:[0,0,1]
	v_fma_mixhi_f16 v179, v47, v181, v179 op_sel:[0,0,1] op_sel_hi:[0,0,1]
	v_add_u32_e32 v176, 0x100010, v176
	v_add_u32_e32 v177, 0x100010, v177
	v_add_u32_e32 v178, 0x100010, v178
	v_add_u32_e32 v179, 0x100010, v179
	v_and_b32_e32 v176, 0xffe0ffe0, v176
	v_and_b32_e32 v177, 0xffe0ffe0, v177
	v_and_b32_e32 v178, 0xffe0ffe0, v178
	v_and_b32_e32 v179, 0xffe0ffe0, v179
	v_add_co_u32_e32 v156, vcc, 0x48000, v134
	v_addc_co_u32_e32 v157, vcc, 0, v135, vcc
	global_store_dwordx4 v[156:157], v[176:179], off
	s_waitcnt vmcnt(11)
	v_pk_mul_f32 v[40:41], v[40:41], s[98:99] op_sel_hi:[1,0]
	v_pk_mul_f32 v[42:43], v[42:43], s[98:99] op_sel_hi:[1,0]
	v_pk_mul_f32 v[36:37], v[36:37], s[98:99] op_sel_hi:[1,0]
	v_pk_mul_f32 v[38:39], v[38:39], s[98:99] op_sel_hi:[1,0]
	v_cvt_f32_ubyte0_e32 v32, v158
	v_cvt_f32_ubyte1_e32 v181, v158
	v_fma_mixlo_f16 v190, v40, v32, v190 op_sel_hi:[0,0,1]
	v_fma_mixhi_f16 v190, v41, v181, v190 op_sel:[0,0,1] op_sel_hi:[0,0,1]
	v_cvt_f32_ubyte2_e32 v32, v158
	v_cvt_f32_ubyte3_e32 v181, v158
	v_fma_mixlo_f16 v191, v42, v32, v191 op_sel_hi:[0,0,1]
	v_fma_mixhi_f16 v191, v43, v181, v191 op_sel:[0,0,1] op_sel_hi:[0,0,1]
	v_cvt_f32_ubyte0_e32 v32, v159
	v_cvt_f32_ubyte1_e32 v181, v159
	v_fma_mixlo_f16 v192, v36, v32, v192 op_sel_hi:[0,0,1]
	v_fma_mixhi_f16 v192, v37, v181, v192 op_sel:[0,0,1] op_sel_hi:[0,0,1]
	v_cvt_f32_ubyte2_e32 v32, v159
	v_cvt_f32_ubyte3_e32 v181, v159
	v_fma_mixlo_f16 v193, v38, v32, v193 op_sel_hi:[0,0,1]
	v_fma_mixhi_f16 v193, v39, v181, v193 op_sel:[0,0,1] op_sel_hi:[0,0,1]
	v_add_u32_e32 v190, 0x100010, v190
	v_add_u32_e32 v191, 0x100010, v191
	v_add_u32_e32 v192, 0x100010, v192
	v_add_u32_e32 v193, 0x100010, v193
	v_and_b32_e32 v190, 0xffe0ffe0, v190
	v_and_b32_e32 v191, 0xffe0ffe0, v191
	v_and_b32_e32 v192, 0xffe0ffe0, v192
	v_and_b32_e32 v193, 0xffe0ffe0, v193
	v_add_co_u32_e32 v158, vcc, 0x48000, v134
	v_addc_co_u32_e32 v159, vcc, 0, v135, vcc
	global_store_dwordx4 v[158:159], v[190:193], off offset:256
	s_waitcnt vmcnt(10)
; template <unsigned D> __device__ __forceinline__ u32x4 rd8(u32x4 w) { w.x = rd<D>(w.x); w.y = rd<D>(w.y); w.z = rd<D>(w.z); w.w = rd<D>(w.w); return w; }
; __device__ __forceinline__ u32x4 pk8(const f32x4 v0, const f32x4 v1) { u32x4 w; w.x = pk_f16(v0[0], v0[1]); w.y = pk_f16(v0[2], v0[3]); w.z = pk_f16(v1[0], v1[1]); w.w = pk_f16(v1[2], v1[3]); return w; }
;     __device__ __forceinline__ void operator()(const f32x4 (&acc)[2][2][4][2], const GUnit& u, int wr, int wc, int fr, int fq, LAS unsigned char* lds) const {
;     ...
;                     for (int bj = 0; bj < 2; ++bj) { const size_t row = (size_t)(grow0 + ai * 128 + m * 16); const int col = gcol0 + bj * 128;
;                         gwv[m][bj] = *(const u32x2*)(sg + row * 2048 + col);
;                         pv[m][bj] = kind == K_Y2 ? *(const u32x4*)(mrg + row * 1024 + col) : (u32x4){0u, 0u, 0u, 0u}; }
;                 asm volatile("" ::: "memory");
; #pragma unroll
;                 for (int m = 0; m < 4; ++m)
; #pragma unroll
;                     for (int bj = 0; bj < 2; ++bj) { const size_t row = (size_t)(grow0 + ai * 128 + m * 16); const int col = gcol0 + bj * 128;
;                         const u32x2 gw = gwv[m][bj]; constexpr float q8 = 1.0f / 255.0f;
;                         const f32x4 g0 = {(float)(gw.x & 255u) * q8, (float)((gw.x >> 8) & 255u) * q8, (float)((gw.x >> 16) & 255u) * q8, (float)(gw.x >> 24) * q8};
;                         const f32x4 g1 = {(float)(gw.y & 255u) * q8, (float)((gw.y >> 8) & 255u) * q8, (float)((gw.y >> 16) & 255u) * q8, (float)(gw.y >> 24) * q8};
;                         f32x4 p0, p1; unpk8(pv[m][bj], p0, p1);
;                         *(u32x4*)(mrg + row * 1024 + col) = rd8<D_AMIX>(pk8(acc[ai][bj][m][0] * g0 + p0, acc[ai][bj][m][1] * g1 + p1)); }
;                 asm volatile("" ::: "memory"); }
	v_pk_mul_f32 v[28:29], v[28:29], s[98:99] op_sel_hi:[1,0]
	v_pk_mul_f32 v[30:31], v[30:31], s[98:99] op_sel_hi:[1,0]
	v_pk_mul_f32 v[24:25], v[24:25], s[98:99] op_sel_hi:[1,0]
	v_pk_mul_f32 v[26:27], v[26:27], s[98:99] op_sel_hi:[1,0]
	v_cvt_f32_ubyte0_e32 v32, v160
	v_cvt_f32_ubyte1_e32 v181, v160
	v_fma_mixlo_f16 v198, v28, v32, v198 op_sel_hi:[0,0,1]
	v_fma_mixhi_f16 v198, v29, v181, v198 op_sel:[0,0,1] op_sel_hi:[0,0,1]
	v_cvt_f32_ubyte2_e32 v32, v160
	v_cvt_f32_ubyte3_e32 v181, v160
	v_fma_mixlo_f16 v199, v30, v32, v199 op_sel_hi:[0,0,1]
	v_fma_mixhi_f16 v199, v31, v181, v199 op_sel:[0,0,1] op_sel_hi:[0,0,1]
	v_cvt_f32_ubyte0_e32 v32, v161
	v_cvt_f32_ubyte1_e32 v181, v161
	v_fma_mixlo_f16 v200, v24, v32, v200 op_sel_hi:[0,0,1]
	v_fma_mixhi_f16 v200, v25, v181, v200 op_sel:[0,0,1] op_sel_hi:[0,0,1]
	v_cvt_f32_ubyte2_e32 v32, v161
	v_cvt_f32_ubyte3_e32 v181, v161
	v_fma_mixlo_f16 v201, v26, v32, v201 op_sel_hi:[0,0,1]
	v_fma_mixhi_f16 v201, v27, v181, v201 op_sel:[0,0,1] op_sel_hi:[0,0,1]
	v_add_u32_e32 v198, 0x100010, v198
	v_add_u32_e32 v199, 0x100010, v199
	v_add_u32_e32 v200, 0x100010, v200
	v_add_u32_e32 v201, 0x100010, v201
	v_and_b32_e32 v198, 0xffe0ffe0, v198
	v_and_b32_e32 v199, 0xffe0ffe0, v199
	v_and_b32_e32 v200, 0xffe0ffe0, v200
	v_and_b32_e32 v201, 0xffe0ffe0, v201
	v_add_co_u32_e32 v160, vcc, 0x50000, v134
	v_addc_co_u32_e32 v161, vcc, 0, v135, vcc
	global_store_dwordx4 v[160:161], v[198:201], off
	s_waitcnt vmcnt(9)
	v_pk_mul_f32 v[20:21], v[20:21], s[98:99] op_sel_hi:[1,0]
	v_pk_mul_f32 v[22:23], v[22:23], s[98:99] op_sel_hi:[1,0]
	v_pk_mul_f32 v[16:17], v[16:17], s[98:99] op_sel_hi:[1,0]
	v_pk_mul_f32 v[18:19], v[18:19], s[98:99] op_sel_hi:[1,0]
	v_cvt_f32_ubyte0_e32 v32, v162
	v_cvt_f32_ubyte1_e32 v181, v162
	v_fma_mixlo_f16 v204, v20, v32, v204 op_sel_hi:[0,0,1]
	v_fma_mixhi_f16 v204, v21, v181, v204 op_sel:[0,0,1] op_sel_hi:[0,0,1]
	v_cvt_f32_ubyte2_e32 v32, v162
	v_cvt_f32_ubyte3_e32 v181, v162
	v_fma_mixlo_f16 v205, v22, v32, v205 op_sel_hi:[0,0,1]
	v_fma_mixhi_f16 v205, v23, v181, v205 op_sel:[0,0,1] op_sel_hi:[0,0,1]
	v_cvt_f32_ubyte0_e32 v32, v163
	v_cvt_f32_ubyte1_e32 v181, v163
	v_fma_mixlo_f16 v206, v16, v32, v206 op_sel_hi:[0,0,1]
	v_fma_mixhi_f16 v206, v17, v181, v206 op_sel:[0,0,1] op_sel_hi:[0,0,1]
	v_cvt_f32_ubyte2_e32 v32, v163
	v_cvt_f32_ubyte3_e32 v181, v163
	v_fma_mixlo_f16 v207, v18, v32, v207 op_sel_hi:[0,0,1]
	v_fma_mixhi_f16 v207, v19, v181, v207 op_sel:[0,0,1] op_sel_hi:[0,0,1]
	v_add_u32_e32 v204, 0x100010, v204
	v_add_u32_e32 v205, 0x100010, v205
	v_add_u32_e32 v206, 0x100010, v206
	v_add_u32_e32 v207, 0x100010, v207
	v_and_b32_e32 v204, 0xffe0ffe0, v204
	v_and_b32_e32 v205, 0xffe0ffe0, v205
	v_and_b32_e32 v206, 0xffe0ffe0, v206
	v_and_b32_e32 v207, 0xffe0ffe0, v207
	v_add_co_u32_e32 v162, vcc, 0x50000, v134
	v_addc_co_u32_e32 v163, vcc, 0, v135, vcc
	global_store_dwordx4 v[162:163], v[204:207], off offset:256
	s_waitcnt vmcnt(8)
	v_pk_mul_f32 v[12:13], v[12:13], s[98:99] op_sel_hi:[1,0]
	v_pk_mul_f32 v[14:15], v[14:15], s[98:99] op_sel_hi:[1,0]
	v_pk_mul_f32 v[8:9], v[8:9], s[98:99] op_sel_hi:[1,0]
	v_pk_mul_f32 v[10:11], v[10:11], s[98:99] op_sel_hi:[1,0]
	v_cvt_f32_ubyte0_e32 v32, v164
	v_cvt_f32_ubyte1_e32 v181, v164
	v_fma_mixlo_f16 v208, v12, v32, v208 op_sel_hi:[0,0,1]
	v_fma_mixhi_f16 v208, v13, v181, v208 op_sel:[0,0,1] op_sel_hi:[0,0,1]
	v_cvt_f32_ubyte2_e32 v32, v164
	v_cvt_f32_ubyte3_e32 v181, v164
	v_fma_mixlo_f16 v209, v14, v32, v209 op_sel_hi:[0,0,1]
	v_fma_mixhi_f16 v209, v15, v181, v209 op_sel:[0,0,1] op_sel_hi:[0,0,1]
	v_cvt_f32_ubyte0_e32 v32, v165
	v_cvt_f32_ubyte1_e32 v181, v165
	v_fma_mixlo_f16 v210, v8, v32, v210 op_sel_hi:[0,0,1]
	v_fma_mixhi_f16 v210, v9, v181, v210 op_sel:[0,0,1] op_sel_hi:[0,0,1]
	v_cvt_f32_ubyte2_e32 v32, v165
	v_cvt_f32_ubyte3_e32 v181, v165
	v_fma_mixlo_f16 v211, v10, v32, v211 op_sel_hi:[0,0,1]
	v_fma_mixhi_f16 v211, v11, v181, v211 op_sel:[0,0,1] op_sel_hi:[0,0,1]
	v_add_u32_e32 v208, 0x100010, v208
	v_add_u32_e32 v209, 0x100010, v209
	v_add_u32_e32 v210, 0x100010, v210
	v_add_u32_e32 v211, 0x100010, v211
	v_and_b32_e32 v208, 0xffe0ffe0, v208
	v_and_b32_e32 v209, 0xffe0ffe0, v209
	v_and_b32_e32 v210, 0xffe0ffe0, v210
	v_and_b32_e32 v211, 0xffe0ffe0, v211
	v_add_co_u32_e32 v164, vcc, 0x58000, v134
	v_addc_co_u32_e32 v165, vcc, 0, v135, vcc
	global_store_dwordx4 v[164:165], v[208:211], off
	s_waitcnt vmcnt(7)
	v_pk_mul_f32 v[4:5], v[4:5], s[98:99] op_sel_hi:[1,0]
	v_pk_mul_f32 v[6:7], v[6:7], s[98:99] op_sel_hi:[1,0]
	v_pk_mul_f32 v[0:1], v[0:1], s[98:99] op_sel_hi:[1,0]
	v_pk_mul_f32 v[2:3], v[2:3], s[98:99] op_sel_hi:[1,0]
	v_cvt_f32_ubyte0_e32 v32, v166
	v_cvt_f32_ubyte1_e32 v181, v166
	v_fma_mixlo_f16 v212, v4, v32, v212 op_sel_hi:[0,0,1]
	v_fma_mixhi_f16 v212, v5, v181, v212 op_sel:[0,0,1] op_sel_hi:[0,0,1]
	v_cvt_f32_ubyte2_e32 v32, v166
	v_cvt_f32_ubyte3_e32 v181, v166
	v_fma_mixlo_f16 v213, v6, v32, v213 op_sel_hi:[0,0,1]
	v_fma_mixhi_f16 v213, v7, v181, v213 op_sel:[0,0,1] op_sel_hi:[0,0,1]
	v_cvt_f32_ubyte0_e32 v32, v167
	v_cvt_f32_ubyte1_e32 v181, v167
	v_fma_mixlo_f16 v214, v0, v32, v214 op_sel_hi:[0,0,1]
	v_fma_mixhi_f16 v214, v1, v181, v214 op_sel:[0,0,1] op_sel_hi:[0,0,1]
	v_cvt_f32_ubyte2_e32 v32, v167
	v_cvt_f32_ubyte3_e32 v181, v167
	v_fma_mixlo_f16 v215, v2, v32, v215 op_sel_hi:[0,0,1]
	v_fma_mixhi_f16 v215, v3, v181, v215 op_sel:[0,0,1] op_sel_hi:[0,0,1]
	v_add_u32_e32 v212, 0x100010, v212
	v_add_u32_e32 v213, 0x100010, v213
	v_add_u32_e32 v214, 0x100010, v214
	v_add_u32_e32 v215, 0x100010, v215
	v_and_b32_e32 v212, 0xffe0ffe0, v212
	v_and_b32_e32 v213, 0xffe0ffe0, v213
	v_and_b32_e32 v214, 0xffe0ffe0, v214
	v_and_b32_e32 v215, 0xffe0ffe0, v215
	v_add_co_u32_e32 v166, vcc, 0x58000, v134
	v_addc_co_u32_e32 v167, vcc, 0, v135, vcc
	global_store_dwordx4 v[166:167], v[212:215], off offset:256
	s_branch .LBB0_300

; template <unsigned D> __device__ __forceinline__ u32x4 rd8(u32x4 w) { w.x = rd<D>(w.x); w.y = rd<D>(w.y); w.z = rd<D>(w.z); w.w = rd<D>(w.w); return w; }
; template <bool F8 = false, class Sched, class Epi>
; __device__ __forceinline__ void gemm_phase(LAS unsigned char* lds, const Sched& S, const Epi& E) {
;     ...
;         if (Epi::keeps_acc(cur.kind)) E.ple_gate(acc, cur, wr, wc, fr, fq);
;         else if (!Epi::after_drain(cur.kind) && !E.skip) E(acc, cur, wr, wc, fr, fq, lds); }
;     __device__ __forceinline__ void operator()(const f32x4 (&acc)[2][2][4][2], const GUnit& u, int wr, int wc, int fr, int fq, LAS unsigned char* lds) const {
;     ...
;         } else if (kind == K_Y1 || kind == K_Y2) {
;             f16* mrg = (f16*)(ws + B_MRG); const unsigned char* sg = (const unsigned char*)(ws + B_SG) + (kind == K_Y2 ? 1024 : 0);
; #pragma unroll
;             for (int ai = 0; ai < 2; ++ai) {
;                 u32x2 gwv[4][2]; u32x4 pv[4][2];
; #pragma unroll
;                 for (int m = 0; m < 4; ++m)
; #pragma unroll
;                     for (int bj = 0; bj < 2; ++bj) { const size_t row = (size_t)(grow0 + ai * 128 + m * 16); const int col = gcol0 + bj * 128;
;                         gwv[m][bj] = *(const u32x2*)(sg + row * 2048 + col);
;                         pv[m][bj] = kind == K_Y2 ? *(const u32x4*)(mrg + row * 1024 + col) : (u32x4){0u, 0u, 0u, 0u}; }
;                 asm volatile("" ::: "memory");
; #pragma unroll
;                 for (int m = 0; m < 4; ++m)
; #pragma unroll
;                     for (int bj = 0; bj < 2; ++bj) { const size_t row = (size_t)(grow0 + ai * 128 + m * 16); const int col = gcol0 + bj * 128;
;                         const u32x2 gw = gwv[m][bj]; constexpr float q8 = 1.0f / 255.0f;
;                         const f32x4 g0 = {(float)(gw.x & 255u) * q8, (float)((gw.x >> 8) & 255u) * q8, (float)((gw.x >> 16) & 255u) * q8, (float)(gw.x >> 24) * q8};
;                         const f32x4 g1 = {(float)(gw.y & 255u) * q8, (float)((gw.y >> 8) & 255u) * q8, (float)((gw.y >> 16) & 255u) * q8, (float)(gw.y >> 24) * q8};
;                         f32x4 p0, p1; unpk8(pv[m][bj], p0, p1);
;                         *(u32x4*)(mrg + row * 1024 + col) = rd8<D_AMIX>(pk8(acc[ai][bj][m][0] * g0 + p0, acc[ai][bj][m][1] * g1 + p1)); }
;                 asm volatile("" ::: "memory"); }
.LBB0_382:
	s_mov_b32 s45, s54
	s_mov_b64 s[78:79], s[52:53]
	v_readlane_b32 s52, v254, 63
	s_mov_b32 s80, s26
	s_mov_b32 s6, s28
	s_mov_b32 s7, s27
	s_mov_b32 s81, s24
	s_mov_b64 s[10:11], s[20:21]
	s_mov_b64 s[8:9], s[22:23]
	s_mov_b64 s[90:91], s[18:19]
	s_mov_b64 s[88:89], s[16:17]
	v_mov_b32_e32 v186, v188
	v_mov_b32_e32 v184, v34
	s_mov_b32 s50, s25
	s_mov_b32 s75, s74
	v_readlane_b32 s53, v255, 0
	v_readlane_b32 s54, v255, 1
	v_readlane_b32 s55, v255, 2
	s_branch .LBB0_174
.LBB0_427:
	s_cmp_eq_u32 s70, 7
	s_cbranch_scc1 .Ldrain_later
	s_cmp_eq_u32 s70, 11
	s_cbranch_scc1 .Ldrain_later
	s_waitcnt vmcnt(0)
